# EpiRes epilogues (out+down GEMM) loads pipelined with counted vmcnt, gate loaded once per unit; gdnprep aup loads batched
# speedup vs baseline: 1.0362x; 1.0212x over previous
; #define G_STAGE(bufoff, gbase, voff) do { _Pragma("unroll") for (int _i = 0; _i < 2; ++_i) \
;     __builtin_amdgcn_global_load_lds((const unsigned*)((const char*)(gbase) + (voff)[_i]), (LAS unsigned*)(lds + (bufoff) + ldsw + _i * 8192), 16, 0, 0); } while (0)
; #define G_LDA(dst, b, h) do { _Pragma("unroll") for (int m = 0; m < 4; ++m) _Pragma("unroll") for (int k = 0; k < 2; ++k) dst[m][k] = *(const LAS bf16x8*)(lds + G_SA(b, h) + aoff + m * 2048 + k * 1024); } while (0)
; #define G_LDB(dst, b, h) do { _Pragma("unroll") for (int n = 0; n < 2; ++n) _Pragma("unroll") for (int k = 0; k < 2; ++k) dst[n][k] = *(const LAS bf16x8*)(lds + G_SB(b, h) + boff + n * 2048 + k * 1024); } while (0)
; #define G_WAIT_V(n) asm volatile("s_waitcnt vmcnt(" #n ")" ::: "memory")
; #define G_WAIT_L(n) asm volatile("s_waitcnt lgkmcnt(" #n ")" ::: "memory")
; #define G_BAR __builtin_amdgcn_s_barrier()
; template <class Epi>
; __device__ __forceinline__ void gemm_phase(LAS unsigned char* lds, const u16* gA, const u16* gBt, int M, int N, int K, const Epi& E) {
;     ...
;     for (int t = 0; t < nt; t += 2) {
;       const bool last = (t == nt - 2);
;       const char* a1 = cA + (size_t)(t + 1) * kstep;
;       const char* a2 = last ? nA : cA + (size_t)(t + 2) * kstep; const char* b2 = last ? nB : cB + (size_t)(t + 2) * kstep;
;       const char* a3 = a2 + kstep; const char* b3 = b2 + kstep;
;       G_LDB(B0, 0, 0); G_SCHED; G_LDA(At, 0, 0); G_STAGE(G_SA(1, 1), a1 + hstep, voffA);
;       G_WAIT_L(8); G_BAR; G_WAIT_L(0); G_MMA(0, 0, At, B0); G_BAR; G_SCHED;
;       G_LDB(B1, 0, 1); G_STAGE(G_SB(0, 0), b2, voffB);
;       G_BAR; G_WAIT_L(0); G_MMA(0, 1, At, B1); G_BAR;
;       G_LDA(At, 0, 1); G_STAGE(G_SA(0, 0), a2, voffA);
;       G_BAR; G_WAIT_L(0); G_MMA(1, 0, At, B0); G_BAR; G_SCHED;
;       G_STAGE(G_SB(0, 1), b2 + hstep, voffB);
;       G_WAIT_V(6); G_BAR; G_MMA(1, 1, At, B1); G_BAR;
;       G_LDB(B0, 1, 0); G_SCHED; G_LDA(At, 1, 0); G_STAGE(G_SA(0, 1), a2 + hstep, voffA);
;       G_WAIT_L(8); G_BAR; G_WAIT_L(0); G_MMA(0, 0, At, B0); G_BAR; G_SCHED;
;       G_LDB(B1, 1, 1); G_STAGE(G_SB(1, 0), b3, voffB);
;       G_BAR; G_WAIT_L(0); G_MMA(0, 1, At, B1); G_BAR;
;       G_LDA(At, 1, 1); G_STAGE(G_SA(1, 0), a3, voffA);
;       G_BAR; G_WAIT_L(0); G_MMA(1, 0, At, B0); G_BAR; G_SCHED;
;       G_STAGE(G_SB(1, 1), b3 + hstep, voffB);
;       G_WAIT_V(6); G_BAR; G_MMA(1, 1, At, B1); G_BAR;
.LBB0_42:
	s_add_u32 s40, s46, 0x100
	s_addc_u32 s41, s47, 0
	s_add_i32 s20, 0, 0x10000
	v_add_u32_e32 v140, s20, v143
	ds_read_b128 v[146:149], v140
	ds_read_b128 v[150:153], v140 offset:1024
	ds_read_b128 v[154:157], v140 offset:2048
	ds_read_b128 v[158:161], v140 offset:3072
	s_cmpk_eq_i32 s31, 0x54
	s_cselect_b32 s51, s1, s41
	s_cselect_b32 s50, s0, s40
	s_cselect_b32 s49, s3, s30
	s_cselect_b32 s48, s2, s27
	v_lshl_add_u64 v[140:141], s[46:47], 0, v[136:137]
	s_add_i32 m0, s54, 0xc000
	ds_read_b128 v[162:165], v145
	ds_read_b128 v[190:193], v145 offset:1024
	ds_read_b128 v[194:197], v145 offset:2048
	ds_read_b128 v[198:201], v145 offset:3072
	ds_read_b128 v[202:205], v145 offset:4096
	ds_read_b128 v[206:209], v145 offset:5120
	ds_read_b128 v[210:213], v145 offset:6144
	ds_read_b128 v[214:217], v145 offset:7168
	global_load_lds_dwordx4 v[140:141], off
	v_lshl_add_u64 v[140:141], s[46:47], 0, v[138:139]
	s_add_i32 m0, s54, 0xe000
	s_nop 0
	global_load_lds_dwordx4 v[140:141], off
	s_waitcnt lgkmcnt(8)
	s_barrier
	s_waitcnt lgkmcnt(0)
	s_setprio 1
	s_waitcnt lgkmcnt(0)
	v_mfma_f32_16x16x32_bf16 v[124:127], v[146:149], v[162:165], v[124:127]
	v_mfma_f32_16x16x32_bf16 v[120:123], v[154:157], v[162:165], v[120:123]
	v_mfma_f32_16x16x32_bf16 v[108:111], v[146:149], v[194:197], v[108:111]
	v_mfma_f32_16x16x32_bf16 v[104:107], v[154:157], v[194:197], v[104:107]
	v_mfma_f32_16x16x32_bf16 v[92:95], v[146:149], v[202:205], v[92:95]
	v_mfma_f32_16x16x32_bf16 v[88:91], v[154:157], v[202:205], v[88:91]
	v_mfma_f32_16x16x32_bf16 v[76:79], v[146:149], v[210:213], v[76:79]
	v_mfma_f32_16x16x32_bf16 v[72:75], v[154:157], v[210:213], v[72:75]
	v_mfma_f32_16x16x32_bf16 v[124:127], v[150:153], v[190:193], v[124:127]
	v_mfma_f32_16x16x32_bf16 v[120:123], v[158:161], v[190:193], v[120:123]
	v_mfma_f32_16x16x32_bf16 v[108:111], v[150:153], v[198:201], v[108:111]
	v_mfma_f32_16x16x32_bf16 v[104:107], v[158:161], v[198:201], v[104:107]
	v_mfma_f32_16x16x32_bf16 v[92:95], v[150:153], v[206:209], v[92:95]
	v_mfma_f32_16x16x32_bf16 v[88:91], v[158:161], v[206:209], v[88:91]
	v_mfma_f32_16x16x32_bf16 v[76:79], v[150:153], v[214:217], v[76:79]
	v_mfma_f32_16x16x32_bf16 v[72:75], v[158:161], v[214:217], v[72:75]
	s_setprio 0
	s_barrier
	s_add_i32 s22, 0, 0x14000
	v_add_u32_e32 v140, s22, v143
	s_add_i32 s20, s20, s53
	ds_read_b128 v[218:221], v140
	ds_read_b128 v[222:225], v140 offset:1024
	ds_read_b128 v[226:229], v140 offset:2048
	ds_read_b128 v[230:233], v140 offset:3072
	v_lshl_add_u64 v[140:141], s[48:49], 0, v[128:129]
	s_mov_b32 m0, s20
	v_lshl_add_u64 v[166:167], s[48:49], 0, v[134:135]
	global_load_lds_dwordx4 v[140:141], off
	s_add_i32 m0, s20, 0x2000
	s_nop 0
	global_load_lds_dwordx4 v[166:167], off
	s_barrier
	s_waitcnt lgkmcnt(0)
	s_setprio 1
	s_waitcnt lgkmcnt(0)
	v_mfma_f32_16x16x32_bf16 v[116:119], v[218:221], v[162:165], v[116:119]
	v_mfma_f32_16x16x32_bf16 v[112:115], v[226:229], v[162:165], v[112:115]
	v_mfma_f32_16x16x32_bf16 v[100:103], v[218:221], v[194:197], v[100:103]
	v_mfma_f32_16x16x32_bf16 v[96:99], v[226:229], v[194:197], v[96:99]
	v_mfma_f32_16x16x32_bf16 v[84:87], v[218:221], v[202:205], v[84:87]
	v_mfma_f32_16x16x32_bf16 v[80:83], v[226:229], v[202:205], v[80:83]
	v_mfma_f32_16x16x32_bf16 v[68:71], v[218:221], v[210:213], v[68:71]
	v_mfma_f32_16x16x32_bf16 v[64:67], v[226:229], v[210:213], v[64:67]
	v_mfma_f32_16x16x32_bf16 v[116:119], v[222:225], v[190:193], v[116:119]
	v_mfma_f32_16x16x32_bf16 v[112:115], v[230:233], v[190:193], v[112:115]
	v_mfma_f32_16x16x32_bf16 v[100:103], v[222:225], v[198:201], v[100:103]
	v_mfma_f32_16x16x32_bf16 v[96:99], v[230:233], v[198:201], v[96:99]
	v_mfma_f32_16x16x32_bf16 v[84:87], v[222:225], v[206:209], v[84:87]
	v_mfma_f32_16x16x32_bf16 v[80:83], v[230:233], v[206:209], v[80:83]
	v_mfma_f32_16x16x32_bf16 v[68:71], v[222:225], v[214:217], v[68:71]
	v_mfma_f32_16x16x32_bf16 v[64:67], v[230:233], v[214:217], v[64:67]
	s_setprio 0
	s_mov_b32 m0, s54
	v_lshl_add_u64 v[234:235], s[50:51], 0, v[128:129]
	s_barrier
	ds_read_b128 v[162:165], v145 offset:16384
	ds_read_b128 v[190:193], v145 offset:17408
	ds_read_b128 v[194:197], v145 offset:18432
	ds_read_b128 v[198:201], v145 offset:19456
	ds_read_b128 v[202:205], v145 offset:20480
	ds_read_b128 v[206:209], v145 offset:21504
	ds_read_b128 v[210:213], v145 offset:22528
	ds_read_b128 v[214:217], v145 offset:23552
	global_load_lds_dwordx4 v[234:235], off
	v_lshl_add_u64 v[236:237], s[50:51], 0, v[134:135]
	s_mov_b32 m0, s55
	s_nop 0
	global_load_lds_dwordx4 v[236:237], off
	s_barrier
	s_waitcnt lgkmcnt(0)
	s_setprio 1
	s_waitcnt lgkmcnt(0)
	v_mfma_f32_16x16x32_bf16 v[60:63], v[146:149], v[162:165], v[60:63]
	v_mfma_f32_16x16x32_bf16 v[56:59], v[154:157], v[162:165], v[56:59]
	v_mfma_f32_16x16x32_bf16 v[44:47], v[146:149], v[194:197], v[44:47]
	v_mfma_f32_16x16x32_bf16 v[40:43], v[154:157], v[194:197], v[40:43]
	v_mfma_f32_16x16x32_bf16 v[28:31], v[146:149], v[202:205], v[28:31]
	v_mfma_f32_16x16x32_bf16 v[24:27], v[154:157], v[202:205], v[24:27]
	v_mfma_f32_16x16x32_bf16 v[12:15], v[146:149], v[210:213], v[12:15]
	v_mfma_f32_16x16x32_bf16 v[8:11], v[154:157], v[210:213], v[8:11]
	v_mfma_f32_16x16x32_bf16 v[60:63], v[150:153], v[190:193], v[60:63]
	v_mfma_f32_16x16x32_bf16 v[56:59], v[158:161], v[190:193], v[56:59]
	v_mfma_f32_16x16x32_bf16 v[44:47], v[150:153], v[198:201], v[44:47]
	v_mfma_f32_16x16x32_bf16 v[40:43], v[158:161], v[198:201], v[40:43]
	v_mfma_f32_16x16x32_bf16 v[28:31], v[150:153], v[206:209], v[28:31]
	v_mfma_f32_16x16x32_bf16 v[24:27], v[158:161], v[206:209], v[24:27]
	v_mfma_f32_16x16x32_bf16 v[12:15], v[150:153], v[214:217], v[12:15]
	v_mfma_f32_16x16x32_bf16 v[8:11], v[158:161], v[214:217], v[8:11]
	s_setprio 0
	s_barrier
; #define G_STAGE(bufoff, gbase, voff) do { _Pragma("unroll") for (int _i = 0; _i < 2; ++_i) \
;     __builtin_amdgcn_global_load_lds((const unsigned*)((const char*)(gbase) + (voff)[_i]), (LAS unsigned*)(lds + (bufoff) + ldsw + _i * 8192), 16, 0, 0); } while (0)
; #define G_LDA(dst, b, h) do { _Pragma("unroll") for (int m = 0; m < 4; ++m) _Pragma("unroll") for (int k = 0; k < 2; ++k) dst[m][k] = *(const LAS bf16x8*)(lds + G_SA(b, h) + aoff + m * 2048 + k * 1024); } while (0)
; #define G_LDB(dst, b, h) do { _Pragma("unroll") for (int n = 0; n < 2; ++n) _Pragma("unroll") for (int k = 0; k < 2; ++k) dst[n][k] = *(const LAS bf16x8*)(lds + G_SB(b, h) + boff + n * 2048 + k * 1024); } while (0)
; #define G_WAIT_V(n) asm volatile("s_waitcnt vmcnt(" #n ")" ::: "memory")
; #define G_WAIT_L(n) asm volatile("s_waitcnt lgkmcnt(" #n ")" ::: "memory")
; #define G_BAR __builtin_amdgcn_s_barrier()
; template <class Epi>
; __device__ __forceinline__ void gemm_phase(LAS unsigned char* lds, const u16* gA, const u16* gBt, int M, int N, int K, const Epi& E) {
;     ...
;     for (int t = 0; t < nt; t += 2) {
;       const bool last = (t == nt - 2);
;       const char* a1 = cA + (size_t)(t + 1) * kstep;
;       const char* a2 = last ? nA : cA + (size_t)(t + 2) * kstep; const char* b2 = last ? nB : cB + (size_t)(t + 2) * kstep;
;       const char* a3 = a2 + kstep; const char* b3 = b2 + kstep;
;       G_LDB(B0, 0, 0); G_SCHED; G_LDA(At, 0, 0); G_STAGE(G_SA(1, 1), a1 + hstep, voffA);
;       G_WAIT_L(8); G_BAR; G_WAIT_L(0); G_MMA(0, 0, At, B0); G_BAR; G_SCHED;
;       G_LDB(B1, 0, 1); G_STAGE(G_SB(0, 0), b2, voffB);
;       G_BAR; G_WAIT_L(0); G_MMA(0, 1, At, B1); G_BAR;
;       G_LDA(At, 0, 1); G_STAGE(G_SA(0, 0), a2, voffA);
;       G_BAR; G_WAIT_L(0); G_MMA(1, 0, At, B0); G_BAR; G_SCHED;
;       G_STAGE(G_SB(0, 1), b2 + hstep, voffB);
;       G_WAIT_V(6); G_BAR; G_MMA(1, 1, At, B1); G_BAR;
;       G_LDB(B0, 1, 0); G_SCHED; G_LDA(At, 1, 0); G_STAGE(G_SA(0, 1), a2 + hstep, voffA);
;       G_WAIT_L(8); G_BAR; G_WAIT_L(0); G_MMA(0, 0, At, B0); G_BAR; G_SCHED;
;       G_LDB(B1, 1, 1); G_STAGE(G_SB(1, 0), b3, voffB);
;       G_BAR; G_WAIT_L(0); G_MMA(0, 1, At, B1); G_BAR;
;       G_LDA(At, 1, 1); G_STAGE(G_SA(1, 0), a3, voffA);
;       G_BAR; G_WAIT_L(0); G_MMA(1, 0, At, B0); G_BAR; G_SCHED;
;       G_STAGE(G_SB(1, 1), b3 + hstep, voffB);
;       G_WAIT_V(6); G_BAR; G_MMA(1, 1, At, B1); G_BAR;
	s_add_u32 s24, s48, 0x160000
	s_addc_u32 s25, s49, 0
	s_add_i32 s20, s22, s53
	v_lshl_add_u64 v[146:147], s[24:25], 0, v[128:129]
	s_mov_b32 m0, s20
	s_nop 0
	global_load_lds_dwordx4 v[146:147], off
	v_lshl_add_u64 v[146:147], s[24:25], 0, v[134:135]
	s_add_i32 m0, s20, 0x2000
	s_nop 0
	global_load_lds_dwordx4 v[146:147], off
	s_waitcnt vmcnt(6)
	s_barrier
	s_setprio 1
	v_mfma_f32_16x16x32_bf16 v[52:55], v[218:221], v[162:165], v[52:55]
	v_mfma_f32_16x16x32_bf16 v[48:51], v[226:229], v[162:165], v[48:51]
	v_mfma_f32_16x16x32_bf16 v[36:39], v[218:221], v[194:197], v[36:39]
	v_mfma_f32_16x16x32_bf16 v[32:35], v[226:229], v[194:197], v[32:35]
	v_mfma_f32_16x16x32_bf16 v[20:23], v[218:221], v[202:205], v[20:23]
	v_mfma_f32_16x16x32_bf16 v[16:19], v[226:229], v[202:205], v[16:19]
	v_mfma_f32_16x16x32_bf16 v[4:7], v[218:221], v[210:213], v[4:7]
	v_mfma_f32_16x16x32_bf16 v[0:3], v[226:229], v[210:213], v[0:3]
	v_mfma_f32_16x16x32_bf16 v[52:55], v[222:225], v[190:193], v[52:55]
	v_mfma_f32_16x16x32_bf16 v[48:51], v[230:233], v[190:193], v[48:51]
	v_mfma_f32_16x16x32_bf16 v[36:39], v[222:225], v[198:201], v[36:39]
	v_mfma_f32_16x16x32_bf16 v[32:35], v[230:233], v[198:201], v[32:35]
	v_mfma_f32_16x16x32_bf16 v[20:23], v[222:225], v[206:209], v[20:23]
	v_mfma_f32_16x16x32_bf16 v[16:19], v[230:233], v[206:209], v[16:19]
	v_mfma_f32_16x16x32_bf16 v[4:7], v[222:225], v[214:217], v[4:7]
	v_mfma_f32_16x16x32_bf16 v[0:3], v[230:233], v[214:217], v[0:3]
	s_setprio 0
	s_add_i32 s20, 0, 0x18000
	v_add_u32_e32 v158, s20, v143
	s_barrier
	ds_read_b128 v[146:149], v158
	ds_read_b128 v[150:153], v158 offset:1024
	ds_read_b128 v[154:157], v158 offset:2048
	ds_read_b128 v[158:161], v158 offset:3072
	s_add_u32 s24, s50, 0x160000
	s_addc_u32 s25, s51, 0
	s_mov_b32 m0, s63
	v_lshl_add_u64 v[218:219], s[24:25], 0, v[128:129]
	ds_read_b128 v[162:165], v145 offset:32768
	ds_read_b128 v[190:193], v145 offset:33792
	ds_read_b128 v[194:197], v145 offset:34816
	ds_read_b128 v[198:201], v145 offset:35840
	ds_read_b128 v[202:205], v145 offset:36864
	ds_read_b128 v[206:209], v145 offset:37888
	ds_read_b128 v[210:213], v145 offset:38912
	ds_read_b128 v[214:217], v145 offset:39936
	global_load_lds_dwordx4 v[218:219], off
	v_lshl_add_u64 v[218:219], s[24:25], 0, v[134:135]
	s_mov_b32 m0, s64
	s_nop 0
	global_load_lds_dwordx4 v[218:219], off
	s_waitcnt lgkmcnt(8)
	s_barrier
	s_waitcnt lgkmcnt(0)
	s_setprio 1
	s_waitcnt lgkmcnt(0)
	v_mfma_f32_16x16x32_bf16 v[124:127], v[146:149], v[162:165], v[124:127]
	v_mfma_f32_16x16x32_bf16 v[120:123], v[154:157], v[162:165], v[120:123]
	v_mfma_f32_16x16x32_bf16 v[108:111], v[146:149], v[194:197], v[108:111]
	v_mfma_f32_16x16x32_bf16 v[104:107], v[154:157], v[194:197], v[104:107]
	v_mfma_f32_16x16x32_bf16 v[92:95], v[146:149], v[202:205], v[92:95]
	v_mfma_f32_16x16x32_bf16 v[88:91], v[154:157], v[202:205], v[88:91]
	v_mfma_f32_16x16x32_bf16 v[76:79], v[146:149], v[210:213], v[76:79]
	v_mfma_f32_16x16x32_bf16 v[72:75], v[154:157], v[210:213], v[72:75]
	v_mfma_f32_16x16x32_bf16 v[124:127], v[150:153], v[190:193], v[124:127]
	v_mfma_f32_16x16x32_bf16 v[120:123], v[158:161], v[190:193], v[120:123]
	v_mfma_f32_16x16x32_bf16 v[108:111], v[150:153], v[198:201], v[108:111]
	v_mfma_f32_16x16x32_bf16 v[104:107], v[158:161], v[198:201], v[104:107]
	v_mfma_f32_16x16x32_bf16 v[92:95], v[150:153], v[206:209], v[92:95]
	v_mfma_f32_16x16x32_bf16 v[88:91], v[158:161], v[206:209], v[88:91]
	v_mfma_f32_16x16x32_bf16 v[76:79], v[150:153], v[214:217], v[76:79]
	v_mfma_f32_16x16x32_bf16 v[72:75], v[158:161], v[214:217], v[72:75]
	s_setprio 0
	s_barrier
	s_add_i32 s22, 0, 0x1c000
	s_add_i32 s20, s20, s53
	v_add_u32_e32 v230, s22, v143
	v_lshl_add_u64 v[140:141], v[140:141], 0, s[34:35]
	s_mov_b32 m0, s20
	ds_read_b128 v[218:221], v230
	ds_read_b128 v[222:225], v230 offset:1024
	ds_read_b128 v[226:229], v230 offset:2048
	ds_read_b128 v[230:233], v230 offset:3072
	global_load_lds_dwordx4 v[140:141], off
	v_lshl_add_u64 v[140:141], v[166:167], 0, s[34:35]
	s_add_i32 m0, s20, 0x2000
	s_nop 0
	global_load_lds_dwordx4 v[140:141], off
	s_barrier
	s_waitcnt lgkmcnt(0)
	s_setprio 1
	s_waitcnt lgkmcnt(0)
	v_mfma_f32_16x16x32_bf16 v[116:119], v[218:221], v[162:165], v[116:119]
	v_mfma_f32_16x16x32_bf16 v[112:115], v[226:229], v[162:165], v[112:115]
	v_mfma_f32_16x16x32_bf16 v[100:103], v[218:221], v[194:197], v[100:103]
	v_mfma_f32_16x16x32_bf16 v[96:99], v[226:229], v[194:197], v[96:99]
	v_mfma_f32_16x16x32_bf16 v[84:87], v[218:221], v[202:205], v[84:87]
	v_mfma_f32_16x16x32_bf16 v[80:83], v[226:229], v[202:205], v[80:83]
	v_mfma_f32_16x16x32_bf16 v[68:71], v[218:221], v[210:213], v[68:71]
	v_mfma_f32_16x16x32_bf16 v[64:67], v[226:229], v[210:213], v[64:67]
	v_mfma_f32_16x16x32_bf16 v[116:119], v[222:225], v[190:193], v[116:119]
	v_mfma_f32_16x16x32_bf16 v[112:115], v[230:233], v[190:193], v[112:115]
	v_mfma_f32_16x16x32_bf16 v[100:103], v[222:225], v[198:201], v[100:103]
	v_mfma_f32_16x16x32_bf16 v[96:99], v[230:233], v[198:201], v[96:99]
	v_mfma_f32_16x16x32_bf16 v[84:87], v[222:225], v[206:209], v[84:87]
	v_mfma_f32_16x16x32_bf16 v[80:83], v[230:233], v[206:209], v[80:83]
	v_mfma_f32_16x16x32_bf16 v[68:71], v[222:225], v[214:217], v[68:71]
	v_mfma_f32_16x16x32_bf16 v[64:67], v[230:233], v[214:217], v[64:67]
	s_setprio 0
	s_mov_b32 m0, s66
	v_lshl_add_u64 v[140:141], v[234:235], 0, s[34:35]
	s_barrier
	ds_read_b128 v[162:165], v145 offset:49152
	ds_read_b128 v[190:193], v145 offset:50176
	ds_read_b128 v[194:197], v145 offset:51200
	ds_read_b128 v[198:201], v145 offset:52224
	ds_read_b128 v[202:205], v145 offset:53248
	ds_read_b128 v[206:209], v145 offset:54272
	ds_read_b128 v[210:213], v145 offset:55296
	ds_read_b128 v[214:217], v145 offset:56320
	global_load_lds_dwordx4 v[140:141], off
	v_lshl_add_u64 v[140:141], v[236:237], 0, s[34:35]
	s_mov_b32 m0, s67
	s_nop 0
	global_load_lds_dwordx4 v[140:141], off
	s_barrier
; #define G_STAGE(bufoff, gbase, voff) do { _Pragma("unroll") for (int _i = 0; _i < 2; ++_i) \
;     __builtin_amdgcn_global_load_lds((const unsigned*)((const char*)(gbase) + (voff)[_i]), (LAS unsigned*)(lds + (bufoff) + ldsw + _i * 8192), 16, 0, 0); } while (0)
; #define G_LDA(dst, b, h) do { _Pragma("unroll") for (int m = 0; m < 4; ++m) _Pragma("unroll") for (int k = 0; k < 2; ++k) dst[m][k] = *(const LAS bf16x8*)(lds + G_SA(b, h) + aoff + m * 2048 + k * 1024); } while (0)
; #define G_BAR __builtin_amdgcn_s_barrier()
;   __device__ __forceinline__ void operator()(const f32x4 (&acc)[2][2][4][2], const Unit& u, int wr, int wc, int fr, int fq) const {
;     const int row0 = u.pm * BM + wr * 64 + fr, col0 = u.pn * BM + wc * 32 + 4 * fq;
; #pragma unroll
;     for (int ai = 0; ai < 2; ++ai)
; #pragma unroll
;       for (int m = 0; m < 4; ++m) {
;         const int row = row0 + ai * HALF + m * 16;
;         const float* gp = gate + (size_t)condof(row) * 6 * D + col0;
;         const float* hold; float* hnew;
;         if (row < NX) { hnew = out + (size_t)row * D + col0; hold = xin ? xin + (size_t)row * D + col0 : hnew; }
;         else { hnew = hc + (size_t)(row - NX) * D + col0; hold = cin ? cin + (size_t)(row - NX) * D + col0 : hnew; }
; #pragma unroll
;         for (int bj = 0; bj < 2; ++bj)
; #pragma unroll
;           for (int n = 0; n < 2; ++n) {
;             f32x4 h = *reinterpret_cast<const f32x4*>(hold + bj * HALF + n * 16);
;             f32x4 g = *reinterpret_cast<const f32x4*>(gp + bj * HALF + n * 16);
;             *reinterpret_cast<f32x4*>(hnew + bj * HALF + n * 16) = h + g * acc[ai][bj][m][n];
;           }
;       }
;   }
; template <class Epi>
; __device__ __forceinline__ void gemm_phase(LAS unsigned char* lds, const u16* gA, const u16* gBt, int M, int N, int K, const Epi& E) {
;     ...
;       G_WAIT_V(6); G_BAR; G_MMA(1, 1, At, B1); G_BAR;
;       G_LDB(B0, 1, 0); G_SCHED; G_LDA(At, 1, 0); G_STAGE(G_SA(0, 1), a2 + hstep, voffA);
;       G_WAIT_L(8); G_BAR; G_WAIT_L(0); G_MMA(0, 0, At, B0); G_BAR; G_SCHED;
;       G_LDB(B1, 1, 1); G_STAGE(G_SB(1, 0), b3, voffB);
;       G_BAR; G_WAIT_L(0); G_MMA(0, 1, At, B1); G_BAR;
;       G_LDA(At, 1, 1); G_STAGE(G_SA(1, 0), a3, voffA);
;       G_BAR; G_WAIT_L(0); G_MMA(1, 0, At, B0); G_BAR; G_SCHED;
;       G_STAGE(G_SB(1, 1), b3 + hstep, voffB);
;       G_WAIT_V(6); G_BAR; G_MMA(1, 1, At, B1); G_BAR;
;     }
	s_waitcnt lgkmcnt(0)
	s_setprio 1
	s_waitcnt lgkmcnt(0)
	v_mfma_f32_16x16x32_bf16 v[60:63], v[146:149], v[162:165], v[60:63]
	v_mfma_f32_16x16x32_bf16 v[56:59], v[154:157], v[162:165], v[56:59]
	v_mfma_f32_16x16x32_bf16 v[44:47], v[146:149], v[194:197], v[44:47]
	v_mfma_f32_16x16x32_bf16 v[40:43], v[154:157], v[194:197], v[40:43]
	v_mfma_f32_16x16x32_bf16 v[28:31], v[146:149], v[202:205], v[28:31]
	v_mfma_f32_16x16x32_bf16 v[24:27], v[154:157], v[202:205], v[24:27]
	v_mfma_f32_16x16x32_bf16 v[12:15], v[146:149], v[210:213], v[12:15]
	v_mfma_f32_16x16x32_bf16 v[8:11], v[154:157], v[210:213], v[8:11]
	v_mfma_f32_16x16x32_bf16 v[60:63], v[150:153], v[190:193], v[60:63]
	v_mfma_f32_16x16x32_bf16 v[56:59], v[158:161], v[190:193], v[56:59]
	v_mfma_f32_16x16x32_bf16 v[44:47], v[150:153], v[198:201], v[44:47]
	v_mfma_f32_16x16x32_bf16 v[40:43], v[158:161], v[198:201], v[40:43]
	v_mfma_f32_16x16x32_bf16 v[28:31], v[150:153], v[206:209], v[28:31]
	v_mfma_f32_16x16x32_bf16 v[24:27], v[158:161], v[206:209], v[24:27]
	v_mfma_f32_16x16x32_bf16 v[12:15], v[150:153], v[214:217], v[12:15]
	v_mfma_f32_16x16x32_bf16 v[8:11], v[158:161], v[214:217], v[8:11]
	s_setprio 0
	s_barrier
	s_add_u32 s24, s48, 0x160080
	s_addc_u32 s25, s49, 0
	s_add_i32 s20, s22, s53
	v_lshl_add_u64 v[140:141], s[24:25], 0, v[128:129]
	s_mov_b32 m0, s20
	s_nop 0
	global_load_lds_dwordx4 v[140:141], off
	v_lshl_add_u64 v[140:141], s[24:25], 0, v[134:135]
	s_add_i32 m0, s20, 0x2000
	s_nop 0
	global_load_lds_dwordx4 v[140:141], off
	s_waitcnt vmcnt(6)
	s_barrier
	s_setprio 1
	v_mfma_f32_16x16x32_bf16 v[52:55], v[218:221], v[162:165], v[52:55]
	v_mfma_f32_16x16x32_bf16 v[48:51], v[226:229], v[162:165], v[48:51]
	v_mfma_f32_16x16x32_bf16 v[36:39], v[218:221], v[194:197], v[36:39]
	v_mfma_f32_16x16x32_bf16 v[32:35], v[226:229], v[194:197], v[32:35]
	v_mfma_f32_16x16x32_bf16 v[20:23], v[218:221], v[202:205], v[20:23]
	v_mfma_f32_16x16x32_bf16 v[16:19], v[226:229], v[202:205], v[16:19]
	v_mfma_f32_16x16x32_bf16 v[4:7], v[218:221], v[210:213], v[4:7]
	v_mfma_f32_16x16x32_bf16 v[0:3], v[226:229], v[210:213], v[0:3]
	v_mfma_f32_16x16x32_bf16 v[52:55], v[222:225], v[190:193], v[52:55]
	v_mfma_f32_16x16x32_bf16 v[48:51], v[230:233], v[190:193], v[48:51]
	v_mfma_f32_16x16x32_bf16 v[36:39], v[222:225], v[198:201], v[36:39]
	v_mfma_f32_16x16x32_bf16 v[32:35], v[230:233], v[198:201], v[32:35]
	v_mfma_f32_16x16x32_bf16 v[20:23], v[222:225], v[206:209], v[20:23]
	v_mfma_f32_16x16x32_bf16 v[16:19], v[230:233], v[206:209], v[16:19]
	v_mfma_f32_16x16x32_bf16 v[4:7], v[222:225], v[214:217], v[4:7]
	v_mfma_f32_16x16x32_bf16 v[0:3], v[230:233], v[214:217], v[0:3]
	s_setprio 0
	s_add_i32 s31, s31, 2
	s_add_u32 s27, s27, 0x100
	s_addc_u32 s30, s30, 0
	s_cmpk_gt_u32 s31, 0x55
	s_mov_b64 s[46:47], s[40:41]
	s_barrier
	s_cbranch_scc0 .LBB0_42
	v_lshl_add_u32 v146, s23, 8, v142
	v_min_i32_e32 v147, 0x4000, v146
	v_lshl_or_b32 v140, s26, 8, v144
	v_ashrrev_i32_e32 v147, 12, v147
	v_ashrrev_i32_e32 v141, 31, v140
	v_mul_hi_i32_i24_e32 v149, 0xc000, v147
	v_mul_i32_i24_e32 v148, 0xc000, v147
	v_lshl_add_u64 v[148:149], s[44:45], 0, v[148:149]
	v_lshlrev_b64 v[140:141], 2, v[140:141]
	s_movk_i32 s20, 0x4000
	v_lshl_add_u64 v[160:161], v[148:149], 0, v[140:141]
	global_load_dwordx4 v[190:193], v[160:161], off
	global_load_dwordx4 v[194:197], v[160:161], off offset:64
	global_load_dwordx4 v[198:201], v[160:161], off offset:512
	global_load_dwordx4 v[202:205], v[160:161], off offset:576
	v_cmp_gt_i32_e32 vcc, s20, v146
	v_add_u32_e32 v147, 0xffffc000, v146
	v_mov_b32_e32 v151, s7
	v_mov_b32_e32 v148, s83
	v_mov_b32_e32 v149, s6
	v_mov_b32_e32 v150, s82
	v_cndmask_b32_e32 v166, v147, v146, vcc
	v_cndmask_b32_e32 v155, v151, v148, vcc
	v_cndmask_b32_e32 v154, v149, v150, vcc
	v_mov_b32_e32 v165, 0
	v_lshl_add_u64 v[162:163], v[154:155], 0, v[140:141]
	s_mov_b32 s26, s70
	s_mov_b32 s23, s71
	s_mov_b64 s[48:49], s[2:3]
	s_mov_b64 s[46:47], s[0:1]
	v_mov_b32_e32 v164, v166
	v_lshlrev_b64 v[152:153], 13, v[164:165]
	v_lshl_add_u64 v[244:245], v[152:153], 0, v[162:163]
	global_load_dwordx4 v[206:209], v[244:245], off
	global_load_dwordx4 v[210:213], v[244:245], off offset:64
	global_load_dwordx4 v[214:217], v[244:245], off offset:512
	global_load_dwordx4 v[218:221], v[244:245], off offset:576
	v_add_u32_e32 v164, 0x10, v166
	v_lshlrev_b64 v[152:153], 13, v[164:165]
	v_lshl_add_u64 v[246:247], v[152:153], 0, v[162:163]
	global_load_dwordx4 v[222:225], v[246:247], off
	global_load_dwordx4 v[226:229], v[246:247], off offset:64
	global_load_dwordx4 v[230:233], v[246:247], off offset:512
	global_load_dwordx4 v[234:237], v[246:247], off offset:576
	v_add_u32_e32 v164, 0x20, v166
	v_lshlrev_b64 v[152:153], 13, v[164:165]
	v_lshl_add_u64 v[248:249], v[152:153], 0, v[162:163]
	v_add_u32_e32 v164, 0x30, v166
	v_lshlrev_b64 v[152:153], 13, v[164:165]
	v_lshl_add_u64 v[250:251], v[152:153], 0, v[162:163]
	v_add_u32_e32 v164, 0x80, v166
	v_lshlrev_b64 v[152:153], 13, v[164:165]
	v_lshl_add_u64 v[252:253], v[152:153], 0, v[162:163]
	v_add_u32_e32 v164, 0x90, v166
	v_lshlrev_b64 v[152:153], 13, v[164:165]
	v_lshl_add_u64 v[254:255], v[152:153], 0, v[162:163]
	v_add_u32_e32 v164, 0xa0, v166
	v_lshlrev_b64 v[152:153], 13, v[164:165]
	v_lshl_add_u64 v[156:157], v[152:153], 0, v[162:163]
	v_add_u32_e32 v164, 0xb0, v166
	v_lshlrev_b64 v[152:153], 13, v[164:165]
	v_lshl_add_u64 v[158:159], v[152:153], 0, v[162:163]
	s_waitcnt vmcnt(4)
;   __device__ __forceinline__ void operator()(const f32x4 (&acc)[2][2][4][2], const Unit& u, int wr, int wc, int fr, int fq) const {
;     const int row0 = u.pm * BM + wr * 64 + fr, col0 = u.pn * BM + wc * 32 + 4 * fq;
; #pragma unroll
;     for (int ai = 0; ai < 2; ++ai)
; #pragma unroll
;       for (int m = 0; m < 4; ++m) {
;         const int row = row0 + ai * HALF + m * 16;
;         const float* gp = gate + (size_t)condof(row) * 6 * D + col0;
;         const float* hold; float* hnew;
;         if (row < NX) { hnew = out + (size_t)row * D + col0; hold = xin ? xin + (size_t)row * D + col0 : hnew; }
;         else { hnew = hc + (size_t)(row - NX) * D + col0; hold = cin ? cin + (size_t)(row - NX) * D + col0 : hnew; }
; #pragma unroll
;         for (int bj = 0; bj < 2; ++bj)
; #pragma unroll
;           for (int n = 0; n < 2; ++n) {
;             f32x4 h = *reinterpret_cast<const f32x4*>(hold + bj * HALF + n * 16);
;             f32x4 g = *reinterpret_cast<const f32x4*>(gp + bj * HALF + n * 16);
;             *reinterpret_cast<f32x4*>(hnew + bj * HALF + n * 16) = h + g * acc[ai][bj][m][n];
;           }
;       }
;   }
	v_pk_fma_f32 v[126:127], v[126:127], v[192:193], v[208:209]
	v_pk_fma_f32 v[124:125], v[124:125], v[190:191], v[206:207]
	v_pk_fma_f32 v[122:123], v[122:123], v[196:197], v[212:213]
	v_pk_fma_f32 v[120:121], v[120:121], v[194:195], v[210:211]
	v_pk_fma_f32 v[118:119], v[118:119], v[200:201], v[216:217]
	v_pk_fma_f32 v[116:117], v[116:117], v[198:199], v[214:215]
	v_pk_fma_f32 v[114:115], v[114:115], v[204:205], v[220:221]
	v_pk_fma_f32 v[112:113], v[112:113], v[202:203], v[218:219]
	global_store_dwordx4 v[244:245], v[124:127], off
	global_store_dwordx4 v[244:245], v[120:123], off offset:64
	global_store_dwordx4 v[244:245], v[116:119], off offset:512
	global_store_dwordx4 v[244:245], v[112:115], off offset:576
	global_load_dwordx4 v[206:209], v[248:249], off
	global_load_dwordx4 v[210:213], v[248:249], off offset:64
	global_load_dwordx4 v[214:217], v[248:249], off offset:512
	global_load_dwordx4 v[218:221], v[248:249], off offset:576
	s_waitcnt vmcnt(4)
	v_pk_fma_f32 v[110:111], v[110:111], v[192:193], v[224:225]
	v_pk_fma_f32 v[108:109], v[108:109], v[190:191], v[222:223]
	v_pk_fma_f32 v[106:107], v[106:107], v[196:197], v[228:229]
	v_pk_fma_f32 v[104:105], v[104:105], v[194:195], v[226:227]
	v_pk_fma_f32 v[102:103], v[102:103], v[200:201], v[232:233]
	v_pk_fma_f32 v[100:101], v[100:101], v[198:199], v[230:231]
	v_pk_fma_f32 v[98:99], v[98:99], v[204:205], v[236:237]
	v_pk_fma_f32 v[96:97], v[96:97], v[202:203], v[234:235]
	global_store_dwordx4 v[246:247], v[108:111], off
	global_store_dwordx4 v[246:247], v[104:107], off offset:64
	global_store_dwordx4 v[246:247], v[100:103], off offset:512
	global_store_dwordx4 v[246:247], v[96:99], off offset:576
	global_load_dwordx4 v[222:225], v[250:251], off
	global_load_dwordx4 v[226:229], v[250:251], off offset:64
	global_load_dwordx4 v[230:233], v[250:251], off offset:512
	global_load_dwordx4 v[234:237], v[250:251], off offset:576
	s_waitcnt vmcnt(4)
	v_pk_fma_f32 v[94:95], v[94:95], v[192:193], v[208:209]
	v_pk_fma_f32 v[92:93], v[92:93], v[190:191], v[206:207]
	v_pk_fma_f32 v[90:91], v[90:91], v[196:197], v[212:213]
	v_pk_fma_f32 v[88:89], v[88:89], v[194:195], v[210:211]
	v_pk_fma_f32 v[86:87], v[86:87], v[200:201], v[216:217]
	v_pk_fma_f32 v[84:85], v[84:85], v[198:199], v[214:215]
	v_pk_fma_f32 v[82:83], v[82:83], v[204:205], v[220:221]
	v_pk_fma_f32 v[80:81], v[80:81], v[202:203], v[218:219]
	global_store_dwordx4 v[248:249], v[92:95], off
	global_store_dwordx4 v[248:249], v[88:91], off offset:64
	global_store_dwordx4 v[248:249], v[84:87], off offset:512
	global_store_dwordx4 v[248:249], v[80:83], off offset:576
	global_load_dwordx4 v[206:209], v[252:253], off
	global_load_dwordx4 v[210:213], v[252:253], off offset:64
	global_load_dwordx4 v[214:217], v[252:253], off offset:512
	global_load_dwordx4 v[218:221], v[252:253], off offset:576
	s_waitcnt vmcnt(4)
	v_pk_fma_f32 v[78:79], v[78:79], v[192:193], v[224:225]
	v_pk_fma_f32 v[76:77], v[76:77], v[190:191], v[222:223]
	v_pk_fma_f32 v[74:75], v[74:75], v[196:197], v[228:229]
	v_pk_fma_f32 v[72:73], v[72:73], v[194:195], v[226:227]
	v_pk_fma_f32 v[70:71], v[70:71], v[200:201], v[232:233]
	v_pk_fma_f32 v[68:69], v[68:69], v[198:199], v[230:231]
	v_pk_fma_f32 v[66:67], v[66:67], v[204:205], v[236:237]
	v_pk_fma_f32 v[64:65], v[64:65], v[202:203], v[234:235]
	global_store_dwordx4 v[250:251], v[76:79], off
	global_store_dwordx4 v[250:251], v[72:75], off offset:64
	global_store_dwordx4 v[250:251], v[68:71], off offset:512
	global_store_dwordx4 v[250:251], v[64:67], off offset:576
	global_load_dwordx4 v[222:225], v[254:255], off
	global_load_dwordx4 v[226:229], v[254:255], off offset:64
	global_load_dwordx4 v[230:233], v[254:255], off offset:512
	global_load_dwordx4 v[234:237], v[254:255], off offset:576
	s_waitcnt vmcnt(4)
	v_pk_fma_f32 v[62:63], v[62:63], v[192:193], v[208:209]
	v_pk_fma_f32 v[60:61], v[60:61], v[190:191], v[206:207]
	v_pk_fma_f32 v[58:59], v[58:59], v[196:197], v[212:213]
	v_pk_fma_f32 v[56:57], v[56:57], v[194:195], v[210:211]
	v_pk_fma_f32 v[54:55], v[54:55], v[200:201], v[216:217]
	v_pk_fma_f32 v[52:53], v[52:53], v[198:199], v[214:215]
	v_pk_fma_f32 v[50:51], v[50:51], v[204:205], v[220:221]
	v_pk_fma_f32 v[48:49], v[48:49], v[202:203], v[218:219]
	global_store_dwordx4 v[252:253], v[60:63], off
	global_store_dwordx4 v[252:253], v[56:59], off offset:64
	global_store_dwordx4 v[252:253], v[52:55], off offset:512
	global_store_dwordx4 v[252:253], v[48:51], off offset:576
	global_load_dwordx4 v[206:209], v[156:157], off
	global_load_dwordx4 v[210:213], v[156:157], off offset:64
	global_load_dwordx4 v[214:217], v[156:157], off offset:512
	global_load_dwordx4 v[218:221], v[156:157], off offset:576
	s_waitcnt vmcnt(4)
	v_pk_fma_f32 v[46:47], v[46:47], v[192:193], v[224:225]
	v_pk_fma_f32 v[44:45], v[44:45], v[190:191], v[222:223]
	v_pk_fma_f32 v[42:43], v[42:43], v[196:197], v[228:229]
	v_pk_fma_f32 v[40:41], v[40:41], v[194:195], v[226:227]
	v_pk_fma_f32 v[38:39], v[38:39], v[200:201], v[232:233]
	v_pk_fma_f32 v[36:37], v[36:37], v[198:199], v[230:231]
	v_pk_fma_f32 v[34:35], v[34:35], v[204:205], v[236:237]
	v_pk_fma_f32 v[32:33], v[32:33], v[202:203], v[234:235]
	global_store_dwordx4 v[254:255], v[44:47], off
	global_store_dwordx4 v[254:255], v[40:43], off offset:64
	global_store_dwordx4 v[254:255], v[36:39], off offset:512
	global_store_dwordx4 v[254:255], v[32:35], off offset:576
	global_load_dwordx4 v[222:225], v[158:159], off
	global_load_dwordx4 v[226:229], v[158:159], off offset:64
	global_load_dwordx4 v[230:233], v[158:159], off offset:512
	global_load_dwordx4 v[234:237], v[158:159], off offset:576
	s_waitcnt vmcnt(4)
	v_pk_fma_f32 v[30:31], v[30:31], v[192:193], v[208:209]
	v_pk_fma_f32 v[28:29], v[28:29], v[190:191], v[206:207]
	v_pk_fma_f32 v[26:27], v[26:27], v[196:197], v[212:213]
	v_pk_fma_f32 v[24:25], v[24:25], v[194:195], v[210:211]
	v_pk_fma_f32 v[22:23], v[22:23], v[200:201], v[216:217]
	v_pk_fma_f32 v[20:21], v[20:21], v[198:199], v[214:215]
	v_pk_fma_f32 v[18:19], v[18:19], v[204:205], v[220:221]
	v_pk_fma_f32 v[16:17], v[16:17], v[202:203], v[218:219]
	global_store_dwordx4 v[156:157], v[28:31], off
	global_store_dwordx4 v[156:157], v[24:27], off offset:64
	global_store_dwordx4 v[156:157], v[20:23], off offset:512
	global_store_dwordx4 v[156:157], v[16:19], off offset:576
	s_waitcnt vmcnt(0)
	v_pk_fma_f32 v[14:15], v[14:15], v[192:193], v[224:225]
	v_pk_fma_f32 v[12:13], v[12:13], v[190:191], v[222:223]
	v_pk_fma_f32 v[10:11], v[10:11], v[196:197], v[228:229]
	v_pk_fma_f32 v[8:9], v[8:9], v[194:195], v[226:227]
	v_pk_fma_f32 v[6:7], v[6:7], v[200:201], v[232:233]
	v_pk_fma_f32 v[4:5], v[4:5], v[198:199], v[230:231]
	v_pk_fma_f32 v[2:3], v[2:3], v[204:205], v[236:237]
	v_pk_fma_f32 v[0:1], v[0:1], v[202:203], v[234:235]
	global_store_dwordx4 v[158:159], v[12:15], off
	global_store_dwordx4 v[158:159], v[8:11], off offset:64
	global_store_dwordx4 v[158:159], v[4:7], off offset:512
	global_store_dwordx4 v[158:159], v[0:3], off offset:576
	s_and_b64 vcc, exec, s[38:39]
	s_cbranch_vccz .LBB0_35
; #define G_WAIT_V(n) asm volatile("s_waitcnt vmcnt(" #n ")" ::: "memory")
; #define G_BAR __builtin_amdgcn_s_barrier()
; template <class Epi>
; __device__ __forceinline__ void gemm_phase(LAS unsigned char* lds, const u16* gA, const u16* gBt, int M, int N, int K, const Epi& E) {
;     ...
;   G_WAIT_V(0);
;   if (wr == 0) G_BAR;
;   G_BAR;
	s_waitcnt vmcnt(0)
	s_cmpk_gt_u32 s52, 0xff
	s_cbranch_scc1 .LBB0_46
	s_barrier

; #define G_STAGE(bufoff, gbase, voff) do { _Pragma("unroll") for (int _i = 0; _i < 2; ++_i) \
;     __builtin_amdgcn_global_load_lds((const unsigned*)((const char*)(gbase) + (voff)[_i]), (LAS unsigned*)(lds + (bufoff) + ldsw + _i * 8192), 16, 0, 0); } while (0)
; #define G_LDA(dst, b, h) do { _Pragma("unroll") for (int m = 0; m < 4; ++m) _Pragma("unroll") for (int k = 0; k < 2; ++k) dst[m][k] = *(const LAS bf16x8*)(lds + G_SA(b, h) + aoff + m * 2048 + k * 1024); } while (0)
; #define G_LDB(dst, b, h) do { _Pragma("unroll") for (int n = 0; n < 2; ++n) _Pragma("unroll") for (int k = 0; k < 2; ++k) dst[n][k] = *(const LAS bf16x8*)(lds + G_SB(b, h) + boff + n * 2048 + k * 1024); } while (0)
; #define G_WAIT_V(n) asm volatile("s_waitcnt vmcnt(" #n ")" ::: "memory")
; #define G_WAIT_L(n) asm volatile("s_waitcnt lgkmcnt(" #n ")" ::: "memory")
; #define G_BAR __builtin_amdgcn_s_barrier()
; template <class Epi>
; __device__ __forceinline__ void gemm_phase(LAS unsigned char* lds, const u16* gA, const u16* gBt, int M, int N, int K, const Epi& E) {
;     ...
;     for (int t = 0; t < nt; t += 2) {
;       const bool last = (t == nt - 2);
;       const char* a1 = cA + (size_t)(t + 1) * kstep;
;       const char* a2 = last ? nA : cA + (size_t)(t + 2) * kstep; const char* b2 = last ? nB : cB + (size_t)(t + 2) * kstep;
;       const char* a3 = a2 + kstep; const char* b3 = b2 + kstep;
;       G_LDB(B0, 0, 0); G_SCHED; G_LDA(At, 0, 0); G_STAGE(G_SA(1, 1), a1 + hstep, voffA);
;       G_WAIT_L(8); G_BAR; G_WAIT_L(0); G_MMA(0, 0, At, B0); G_BAR; G_SCHED;
;       G_LDB(B1, 0, 1); G_STAGE(G_SB(0, 0), b2, voffB);
;       G_BAR; G_WAIT_L(0); G_MMA(0, 1, At, B1); G_BAR;
;       G_LDA(At, 0, 1); G_STAGE(G_SA(0, 0), a2, voffA);
;       G_BAR; G_WAIT_L(0); G_MMA(1, 0, At, B0); G_BAR; G_SCHED;
;       G_STAGE(G_SB(0, 1), b2 + hstep, voffB);
;       G_WAIT_V(6); G_BAR; G_MMA(1, 1, At, B1); G_BAR;
;       G_LDB(B0, 1, 0); G_SCHED; G_LDA(At, 1, 0); G_STAGE(G_SA(0, 1), a2 + hstep, voffA);
;       G_WAIT_L(8); G_BAR; G_WAIT_L(0); G_MMA(0, 0, At, B0); G_BAR; G_SCHED;
;       G_LDB(B1, 1, 1); G_STAGE(G_SB(1, 0), b3, voffB);
;       G_BAR; G_WAIT_L(0); G_MMA(0, 1, At, B1); G_BAR;
;       G_LDA(At, 1, 1); G_STAGE(G_SA(1, 0), a3, voffA);
;       G_BAR; G_WAIT_L(0); G_MMA(1, 0, At, B0); G_BAR; G_SCHED;
;       G_STAGE(G_SB(1, 1), b3 + hstep, voffB);
;       G_WAIT_V(6); G_BAR; G_MMA(1, 1, At, B1); G_BAR;
.LBB0_81:
	s_add_u32 s48, s46, 0x100
	s_addc_u32 s49, s47, 0
	s_add_i32 s20, 0, 0x10000
	v_add_u32_e32 v140, s20, v143
	ds_read_b128 v[146:149], v140
	ds_read_b128 v[150:153], v140 offset:1024
	ds_read_b128 v[154:157], v140 offset:2048
	ds_read_b128 v[158:161], v140 offset:3072
	s_cmp_eq_u32 s37, 28
	s_cselect_b32 s53, s26, s49
	s_cselect_b32 s52, s27, s48
	s_cselect_b32 s51, s3, s33
	s_cselect_b32 s50, s30, s31
	v_lshl_add_u64 v[140:141], s[46:47], 0, v[136:137]
	s_add_i32 m0, s45, 0xc000
	ds_read_b128 v[162:165], v145
	ds_read_b128 v[190:193], v145 offset:1024
	ds_read_b128 v[194:197], v145 offset:2048
	ds_read_b128 v[198:201], v145 offset:3072
	ds_read_b128 v[202:205], v145 offset:4096
	ds_read_b128 v[206:209], v145 offset:5120
	ds_read_b128 v[210:213], v145 offset:6144
	ds_read_b128 v[214:217], v145 offset:7168
	global_load_lds_dwordx4 v[140:141], off
	v_lshl_add_u64 v[140:141], s[46:47], 0, v[138:139]
	s_add_i32 m0, s45, 0xe000
	s_nop 0
	global_load_lds_dwordx4 v[140:141], off
	s_waitcnt lgkmcnt(8)
	s_barrier
	s_waitcnt lgkmcnt(0)
	s_setprio 1
	s_waitcnt lgkmcnt(0)
	v_mfma_f32_16x16x32_bf16 v[124:127], v[146:149], v[162:165], v[124:127]
	v_mfma_f32_16x16x32_bf16 v[120:123], v[154:157], v[162:165], v[120:123]
	v_mfma_f32_16x16x32_bf16 v[108:111], v[146:149], v[194:197], v[108:111]
	v_mfma_f32_16x16x32_bf16 v[104:107], v[154:157], v[194:197], v[104:107]
	v_mfma_f32_16x16x32_bf16 v[92:95], v[146:149], v[202:205], v[92:95]
	v_mfma_f32_16x16x32_bf16 v[88:91], v[154:157], v[202:205], v[88:91]
	v_mfma_f32_16x16x32_bf16 v[76:79], v[146:149], v[210:213], v[76:79]
	v_mfma_f32_16x16x32_bf16 v[72:75], v[154:157], v[210:213], v[72:75]
	v_mfma_f32_16x16x32_bf16 v[124:127], v[150:153], v[190:193], v[124:127]
	v_mfma_f32_16x16x32_bf16 v[120:123], v[158:161], v[190:193], v[120:123]
	v_mfma_f32_16x16x32_bf16 v[108:111], v[150:153], v[198:201], v[108:111]
	v_mfma_f32_16x16x32_bf16 v[104:107], v[158:161], v[198:201], v[104:107]
	v_mfma_f32_16x16x32_bf16 v[92:95], v[150:153], v[206:209], v[92:95]
	v_mfma_f32_16x16x32_bf16 v[88:91], v[158:161], v[206:209], v[88:91]
	v_mfma_f32_16x16x32_bf16 v[76:79], v[150:153], v[214:217], v[76:79]
	v_mfma_f32_16x16x32_bf16 v[72:75], v[158:161], v[214:217], v[72:75]
	s_setprio 0
	s_barrier
	s_add_i32 s22, 0, 0x14000
	v_add_u32_e32 v140, s22, v143
	s_add_i32 s20, s20, s55
	ds_read_b128 v[218:221], v140
	ds_read_b128 v[222:225], v140 offset:1024
	ds_read_b128 v[226:229], v140 offset:2048
	ds_read_b128 v[230:233], v140 offset:3072
	v_lshl_add_u64 v[140:141], s[50:51], 0, v[128:129]
	s_mov_b32 m0, s20
	v_lshl_add_u64 v[166:167], s[50:51], 0, v[134:135]
	global_load_lds_dwordx4 v[140:141], off
	s_add_i32 m0, s20, 0x2000
	s_nop 0
	global_load_lds_dwordx4 v[166:167], off
	s_barrier
	s_waitcnt lgkmcnt(0)
	s_setprio 1
	s_waitcnt lgkmcnt(0)
	v_mfma_f32_16x16x32_bf16 v[116:119], v[218:221], v[162:165], v[116:119]
	v_mfma_f32_16x16x32_bf16 v[112:115], v[226:229], v[162:165], v[112:115]
	v_mfma_f32_16x16x32_bf16 v[100:103], v[218:221], v[194:197], v[100:103]
	v_mfma_f32_16x16x32_bf16 v[96:99], v[226:229], v[194:197], v[96:99]
	v_mfma_f32_16x16x32_bf16 v[84:87], v[218:221], v[202:205], v[84:87]
	v_mfma_f32_16x16x32_bf16 v[80:83], v[226:229], v[202:205], v[80:83]
	v_mfma_f32_16x16x32_bf16 v[68:71], v[218:221], v[210:213], v[68:71]
	v_mfma_f32_16x16x32_bf16 v[64:67], v[226:229], v[210:213], v[64:67]
	v_mfma_f32_16x16x32_bf16 v[116:119], v[222:225], v[190:193], v[116:119]
	v_mfma_f32_16x16x32_bf16 v[112:115], v[230:233], v[190:193], v[112:115]
	v_mfma_f32_16x16x32_bf16 v[100:103], v[222:225], v[198:201], v[100:103]
	v_mfma_f32_16x16x32_bf16 v[96:99], v[230:233], v[198:201], v[96:99]
	v_mfma_f32_16x16x32_bf16 v[84:87], v[222:225], v[206:209], v[84:87]
	v_mfma_f32_16x16x32_bf16 v[80:83], v[230:233], v[206:209], v[80:83]
	v_mfma_f32_16x16x32_bf16 v[68:71], v[222:225], v[214:217], v[68:71]
	v_mfma_f32_16x16x32_bf16 v[64:67], v[230:233], v[214:217], v[64:67]
	s_setprio 0
	s_mov_b32 m0, s45
	v_lshl_add_u64 v[234:235], s[52:53], 0, v[128:129]
	s_barrier
	ds_read_b128 v[162:165], v145 offset:16384
	ds_read_b128 v[190:193], v145 offset:17408
	ds_read_b128 v[194:197], v145 offset:18432
	ds_read_b128 v[198:201], v145 offset:19456
	ds_read_b128 v[202:205], v145 offset:20480
	ds_read_b128 v[206:209], v145 offset:21504
	ds_read_b128 v[210:213], v145 offset:22528
	ds_read_b128 v[214:217], v145 offset:23552
	global_load_lds_dwordx4 v[234:235], off
	v_lshl_add_u64 v[236:237], s[52:53], 0, v[134:135]
	s_mov_b32 m0, s60
	s_nop 0
	global_load_lds_dwordx4 v[236:237], off
	s_barrier
	s_waitcnt lgkmcnt(0)
	s_setprio 1
	s_waitcnt lgkmcnt(0)
	v_mfma_f32_16x16x32_bf16 v[60:63], v[146:149], v[162:165], v[60:63]
	v_mfma_f32_16x16x32_bf16 v[56:59], v[154:157], v[162:165], v[56:59]
	v_mfma_f32_16x16x32_bf16 v[44:47], v[146:149], v[194:197], v[44:47]
	v_mfma_f32_16x16x32_bf16 v[40:43], v[154:157], v[194:197], v[40:43]
	v_mfma_f32_16x16x32_bf16 v[28:31], v[146:149], v[202:205], v[28:31]
	v_mfma_f32_16x16x32_bf16 v[24:27], v[154:157], v[202:205], v[24:27]
	v_mfma_f32_16x16x32_bf16 v[12:15], v[146:149], v[210:213], v[12:15]
	v_mfma_f32_16x16x32_bf16 v[8:11], v[154:157], v[210:213], v[8:11]
	v_mfma_f32_16x16x32_bf16 v[60:63], v[150:153], v[190:193], v[60:63]
	v_mfma_f32_16x16x32_bf16 v[56:59], v[158:161], v[190:193], v[56:59]
	v_mfma_f32_16x16x32_bf16 v[44:47], v[150:153], v[198:201], v[44:47]
	v_mfma_f32_16x16x32_bf16 v[40:43], v[158:161], v[198:201], v[40:43]
	v_mfma_f32_16x16x32_bf16 v[28:31], v[150:153], v[206:209], v[28:31]
	v_mfma_f32_16x16x32_bf16 v[24:27], v[158:161], v[206:209], v[24:27]
	v_mfma_f32_16x16x32_bf16 v[12:15], v[150:153], v[214:217], v[12:15]
	v_mfma_f32_16x16x32_bf16 v[8:11], v[158:161], v[214:217], v[8:11]
	s_setprio 0
	s_barrier
; #define G_STAGE(bufoff, gbase, voff) do { _Pragma("unroll") for (int _i = 0; _i < 2; ++_i) \
;     __builtin_amdgcn_global_load_lds((const unsigned*)((const char*)(gbase) + (voff)[_i]), (LAS unsigned*)(lds + (bufoff) + ldsw + _i * 8192), 16, 0, 0); } while (0)
; #define G_LDA(dst, b, h) do { _Pragma("unroll") for (int m = 0; m < 4; ++m) _Pragma("unroll") for (int k = 0; k < 2; ++k) dst[m][k] = *(const LAS bf16x8*)(lds + G_SA(b, h) + aoff + m * 2048 + k * 1024); } while (0)
; #define G_LDB(dst, b, h) do { _Pragma("unroll") for (int n = 0; n < 2; ++n) _Pragma("unroll") for (int k = 0; k < 2; ++k) dst[n][k] = *(const LAS bf16x8*)(lds + G_SB(b, h) + boff + n * 2048 + k * 1024); } while (0)
; #define G_WAIT_V(n) asm volatile("s_waitcnt vmcnt(" #n ")" ::: "memory")
; #define G_WAIT_L(n) asm volatile("s_waitcnt lgkmcnt(" #n ")" ::: "memory")
; #define G_BAR __builtin_amdgcn_s_barrier()
; template <class Epi>
; __device__ __forceinline__ void gemm_phase(LAS unsigned char* lds, const u16* gA, const u16* gBt, int M, int N, int K, const Epi& E) {
;     ...
;     for (int t = 0; t < nt; t += 2) {
;       const bool last = (t == nt - 2);
;       const char* a1 = cA + (size_t)(t + 1) * kstep;
;       const char* a2 = last ? nA : cA + (size_t)(t + 2) * kstep; const char* b2 = last ? nB : cB + (size_t)(t + 2) * kstep;
;       const char* a3 = a2 + kstep; const char* b3 = b2 + kstep;
;       G_LDB(B0, 0, 0); G_SCHED; G_LDA(At, 0, 0); G_STAGE(G_SA(1, 1), a1 + hstep, voffA);
;       G_WAIT_L(8); G_BAR; G_WAIT_L(0); G_MMA(0, 0, At, B0); G_BAR; G_SCHED;
;       G_LDB(B1, 0, 1); G_STAGE(G_SB(0, 0), b2, voffB);
;       G_BAR; G_WAIT_L(0); G_MMA(0, 1, At, B1); G_BAR;
;       G_LDA(At, 0, 1); G_STAGE(G_SA(0, 0), a2, voffA);
;       G_BAR; G_WAIT_L(0); G_MMA(1, 0, At, B0); G_BAR; G_SCHED;
;       G_STAGE(G_SB(0, 1), b2 + hstep, voffB);
;       G_WAIT_V(6); G_BAR; G_MMA(1, 1, At, B1); G_BAR;
;       G_LDB(B0, 1, 0); G_SCHED; G_LDA(At, 1, 0); G_STAGE(G_SA(0, 1), a2 + hstep, voffA);
;       G_WAIT_L(8); G_BAR; G_WAIT_L(0); G_MMA(0, 0, At, B0); G_BAR; G_SCHED;
;       G_LDB(B1, 1, 1); G_STAGE(G_SB(1, 0), b3, voffB);
;       G_BAR; G_WAIT_L(0); G_MMA(0, 1, At, B1); G_BAR;
;       G_LDA(At, 1, 1); G_STAGE(G_SA(1, 0), a3, voffA);
;       G_BAR; G_WAIT_L(0); G_MMA(1, 0, At, B0); G_BAR; G_SCHED;
;       G_STAGE(G_SB(1, 1), b3 + hstep, voffB);
;       G_WAIT_V(6); G_BAR; G_MMA(1, 1, At, B1); G_BAR;
	s_add_u32 s24, s50, 0x80000
	s_addc_u32 s25, s51, 0
	s_add_i32 s20, s22, s55
	v_lshl_add_u64 v[146:147], s[24:25], 0, v[128:129]
	s_mov_b32 m0, s20
	s_nop 0
	global_load_lds_dwordx4 v[146:147], off
	v_lshl_add_u64 v[146:147], s[24:25], 0, v[134:135]
	s_add_i32 m0, s20, 0x2000
	s_nop 0
	global_load_lds_dwordx4 v[146:147], off
	s_waitcnt vmcnt(6)
	s_barrier
	s_setprio 1
	v_mfma_f32_16x16x32_bf16 v[52:55], v[218:221], v[162:165], v[52:55]
	v_mfma_f32_16x16x32_bf16 v[48:51], v[226:229], v[162:165], v[48:51]
	v_mfma_f32_16x16x32_bf16 v[36:39], v[218:221], v[194:197], v[36:39]
	v_mfma_f32_16x16x32_bf16 v[32:35], v[226:229], v[194:197], v[32:35]
	v_mfma_f32_16x16x32_bf16 v[20:23], v[218:221], v[202:205], v[20:23]
	v_mfma_f32_16x16x32_bf16 v[16:19], v[226:229], v[202:205], v[16:19]
	v_mfma_f32_16x16x32_bf16 v[4:7], v[218:221], v[210:213], v[4:7]
	v_mfma_f32_16x16x32_bf16 v[0:3], v[226:229], v[210:213], v[0:3]
	v_mfma_f32_16x16x32_bf16 v[52:55], v[222:225], v[190:193], v[52:55]
	v_mfma_f32_16x16x32_bf16 v[48:51], v[230:233], v[190:193], v[48:51]
	v_mfma_f32_16x16x32_bf16 v[36:39], v[222:225], v[198:201], v[36:39]
	v_mfma_f32_16x16x32_bf16 v[32:35], v[230:233], v[198:201], v[32:35]
	v_mfma_f32_16x16x32_bf16 v[20:23], v[222:225], v[206:209], v[20:23]
	v_mfma_f32_16x16x32_bf16 v[16:19], v[230:233], v[206:209], v[16:19]
	v_mfma_f32_16x16x32_bf16 v[4:7], v[222:225], v[214:217], v[4:7]
	v_mfma_f32_16x16x32_bf16 v[0:3], v[230:233], v[214:217], v[0:3]
	s_setprio 0
	s_add_i32 s20, 0, 0x18000
	v_add_u32_e32 v158, s20, v143
	s_barrier
	ds_read_b128 v[146:149], v158
	ds_read_b128 v[150:153], v158 offset:1024
	ds_read_b128 v[154:157], v158 offset:2048
	ds_read_b128 v[158:161], v158 offset:3072
	s_add_u32 s24, s52, 0x80000
	s_addc_u32 s25, s53, 0
	s_mov_b32 m0, s61
	v_lshl_add_u64 v[218:219], s[24:25], 0, v[128:129]
	ds_read_b128 v[162:165], v145 offset:32768
	ds_read_b128 v[190:193], v145 offset:33792
	ds_read_b128 v[194:197], v145 offset:34816
	ds_read_b128 v[198:201], v145 offset:35840
	ds_read_b128 v[202:205], v145 offset:36864
	ds_read_b128 v[206:209], v145 offset:37888
	ds_read_b128 v[210:213], v145 offset:38912
	ds_read_b128 v[214:217], v145 offset:39936
	global_load_lds_dwordx4 v[218:219], off
	v_lshl_add_u64 v[218:219], s[24:25], 0, v[134:135]
	s_mov_b32 m0, s62
	s_nop 0
	global_load_lds_dwordx4 v[218:219], off
	s_waitcnt lgkmcnt(8)
	s_barrier
	s_waitcnt lgkmcnt(0)
	s_setprio 1
	s_waitcnt lgkmcnt(0)
	v_mfma_f32_16x16x32_bf16 v[124:127], v[146:149], v[162:165], v[124:127]
	v_mfma_f32_16x16x32_bf16 v[120:123], v[154:157], v[162:165], v[120:123]
	v_mfma_f32_16x16x32_bf16 v[108:111], v[146:149], v[194:197], v[108:111]
	v_mfma_f32_16x16x32_bf16 v[104:107], v[154:157], v[194:197], v[104:107]
	v_mfma_f32_16x16x32_bf16 v[92:95], v[146:149], v[202:205], v[92:95]
	v_mfma_f32_16x16x32_bf16 v[88:91], v[154:157], v[202:205], v[88:91]
	v_mfma_f32_16x16x32_bf16 v[76:79], v[146:149], v[210:213], v[76:79]
	v_mfma_f32_16x16x32_bf16 v[72:75], v[154:157], v[210:213], v[72:75]
	v_mfma_f32_16x16x32_bf16 v[124:127], v[150:153], v[190:193], v[124:127]
	v_mfma_f32_16x16x32_bf16 v[120:123], v[158:161], v[190:193], v[120:123]
	v_mfma_f32_16x16x32_bf16 v[108:111], v[150:153], v[198:201], v[108:111]
	v_mfma_f32_16x16x32_bf16 v[104:107], v[158:161], v[198:201], v[104:107]
	v_mfma_f32_16x16x32_bf16 v[92:95], v[150:153], v[206:209], v[92:95]
	v_mfma_f32_16x16x32_bf16 v[88:91], v[158:161], v[206:209], v[88:91]
	v_mfma_f32_16x16x32_bf16 v[76:79], v[150:153], v[214:217], v[76:79]
	v_mfma_f32_16x16x32_bf16 v[72:75], v[158:161], v[214:217], v[72:75]
	s_setprio 0
	s_barrier
	s_add_i32 s22, 0, 0x1c000
	s_add_i32 s20, s20, s55
	v_add_u32_e32 v230, s22, v143
	v_lshl_add_u64 v[140:141], v[140:141], 0, s[34:35]
	s_mov_b32 m0, s20
	ds_read_b128 v[218:221], v230
	ds_read_b128 v[222:225], v230 offset:1024
	ds_read_b128 v[226:229], v230 offset:2048
	ds_read_b128 v[230:233], v230 offset:3072
	global_load_lds_dwordx4 v[140:141], off
	v_lshl_add_u64 v[140:141], v[166:167], 0, s[34:35]
	s_add_i32 m0, s20, 0x2000
	s_nop 0
	global_load_lds_dwordx4 v[140:141], off
	s_barrier
	s_waitcnt lgkmcnt(0)
	s_setprio 1
	s_waitcnt lgkmcnt(0)
	v_mfma_f32_16x16x32_bf16 v[116:119], v[218:221], v[162:165], v[116:119]
	v_mfma_f32_16x16x32_bf16 v[112:115], v[226:229], v[162:165], v[112:115]
	v_mfma_f32_16x16x32_bf16 v[100:103], v[218:221], v[194:197], v[100:103]
	v_mfma_f32_16x16x32_bf16 v[96:99], v[226:229], v[194:197], v[96:99]
	v_mfma_f32_16x16x32_bf16 v[84:87], v[218:221], v[202:205], v[84:87]
	v_mfma_f32_16x16x32_bf16 v[80:83], v[226:229], v[202:205], v[80:83]
	v_mfma_f32_16x16x32_bf16 v[68:71], v[218:221], v[210:213], v[68:71]
	v_mfma_f32_16x16x32_bf16 v[64:67], v[226:229], v[210:213], v[64:67]
	v_mfma_f32_16x16x32_bf16 v[116:119], v[222:225], v[190:193], v[116:119]
	v_mfma_f32_16x16x32_bf16 v[112:115], v[230:233], v[190:193], v[112:115]
	v_mfma_f32_16x16x32_bf16 v[100:103], v[222:225], v[198:201], v[100:103]
	v_mfma_f32_16x16x32_bf16 v[96:99], v[230:233], v[198:201], v[96:99]
	v_mfma_f32_16x16x32_bf16 v[84:87], v[222:225], v[206:209], v[84:87]
	v_mfma_f32_16x16x32_bf16 v[80:83], v[230:233], v[206:209], v[80:83]
	v_mfma_f32_16x16x32_bf16 v[68:71], v[222:225], v[214:217], v[68:71]
	v_mfma_f32_16x16x32_bf16 v[64:67], v[230:233], v[214:217], v[64:67]
	s_setprio 0
	s_mov_b32 m0, s67
	v_lshl_add_u64 v[140:141], v[234:235], 0, s[34:35]
	s_barrier
	ds_read_b128 v[162:165], v145 offset:49152
	ds_read_b128 v[190:193], v145 offset:50176
	ds_read_b128 v[194:197], v145 offset:51200
	ds_read_b128 v[198:201], v145 offset:52224
	ds_read_b128 v[202:205], v145 offset:53248
	ds_read_b128 v[206:209], v145 offset:54272
	ds_read_b128 v[210:213], v145 offset:55296
	ds_read_b128 v[214:217], v145 offset:56320
	global_load_lds_dwordx4 v[140:141], off
	v_lshl_add_u64 v[140:141], v[236:237], 0, s[34:35]
	s_mov_b32 m0, s68
	s_nop 0
	global_load_lds_dwordx4 v[140:141], off
	s_barrier
;   __device__ __forceinline__ void operator()(const f32x4 (&acc)[2][2][4][2], const Unit& u, int wr, int wc, int fr, int fq) const {
;     const int row0 = u.pm * BM + wr * 64 + fr, col0 = u.pn * BM + wc * 32 + 4 * fq;
; #pragma unroll
;     for (int ai = 0; ai < 2; ++ai)
; #pragma unroll
;       for (int m = 0; m < 4; ++m) {
;         const int row = row0 + ai * HALF + m * 16;
;         const float* gp = gate + (size_t)condof(row) * 6 * D + col0;
;         const float* hold; float* hnew;
;         if (row < NX) { hnew = out + (size_t)row * D + col0; hold = xin ? xin + (size_t)row * D + col0 : hnew; }
;         else { hnew = hc + (size_t)(row - NX) * D + col0; hold = cin ? cin + (size_t)(row - NX) * D + col0 : hnew; }
; #pragma unroll
;         for (int bj = 0; bj < 2; ++bj)
; #pragma unroll
;           for (int n = 0; n < 2; ++n) {
;             f32x4 h = *reinterpret_cast<const f32x4*>(hold + bj * HALF + n * 16);
;             f32x4 g = *reinterpret_cast<const f32x4*>(gp + bj * HALF + n * 16);
;             *reinterpret_cast<f32x4*>(hnew + bj * HALF + n * 16) = h + g * acc[ai][bj][m][n];
;           }
;       }
;   }
	s_waitcnt lgkmcnt(0)
	s_setprio 1
	s_waitcnt lgkmcnt(0)
	v_mfma_f32_16x16x32_bf16 v[60:63], v[146:149], v[162:165], v[60:63]
	v_mfma_f32_16x16x32_bf16 v[56:59], v[154:157], v[162:165], v[56:59]
	v_mfma_f32_16x16x32_bf16 v[44:47], v[146:149], v[194:197], v[44:47]
	v_mfma_f32_16x16x32_bf16 v[40:43], v[154:157], v[194:197], v[40:43]
	v_mfma_f32_16x16x32_bf16 v[28:31], v[146:149], v[202:205], v[28:31]
	v_mfma_f32_16x16x32_bf16 v[24:27], v[154:157], v[202:205], v[24:27]
	v_mfma_f32_16x16x32_bf16 v[12:15], v[146:149], v[210:213], v[12:15]
	v_mfma_f32_16x16x32_bf16 v[8:11], v[154:157], v[210:213], v[8:11]
	v_mfma_f32_16x16x32_bf16 v[60:63], v[150:153], v[190:193], v[60:63]
	v_mfma_f32_16x16x32_bf16 v[56:59], v[158:161], v[190:193], v[56:59]
	v_mfma_f32_16x16x32_bf16 v[44:47], v[150:153], v[198:201], v[44:47]
	v_mfma_f32_16x16x32_bf16 v[40:43], v[158:161], v[198:201], v[40:43]
	v_mfma_f32_16x16x32_bf16 v[28:31], v[150:153], v[206:209], v[28:31]
	v_mfma_f32_16x16x32_bf16 v[24:27], v[158:161], v[206:209], v[24:27]
	v_mfma_f32_16x16x32_bf16 v[12:15], v[150:153], v[214:217], v[12:15]
	v_mfma_f32_16x16x32_bf16 v[8:11], v[158:161], v[214:217], v[8:11]
	s_setprio 0
	s_barrier
	s_add_u32 s24, s50, 0x80080
	s_addc_u32 s25, s51, 0
	s_add_i32 s20, s22, s55
	v_lshl_add_u64 v[140:141], s[24:25], 0, v[128:129]
	s_mov_b32 m0, s20
	s_nop 0
	global_load_lds_dwordx4 v[140:141], off
	v_lshl_add_u64 v[140:141], s[24:25], 0, v[134:135]
	s_add_i32 m0, s20, 0x2000
	s_nop 0
	global_load_lds_dwordx4 v[140:141], off
	s_waitcnt vmcnt(6)
	s_barrier
	s_setprio 1
	v_mfma_f32_16x16x32_bf16 v[52:55], v[218:221], v[162:165], v[52:55]
	v_mfma_f32_16x16x32_bf16 v[48:51], v[226:229], v[162:165], v[48:51]
	v_mfma_f32_16x16x32_bf16 v[36:39], v[218:221], v[194:197], v[36:39]
	v_mfma_f32_16x16x32_bf16 v[32:35], v[226:229], v[194:197], v[32:35]
	v_mfma_f32_16x16x32_bf16 v[20:23], v[218:221], v[202:205], v[20:23]
	v_mfma_f32_16x16x32_bf16 v[16:19], v[226:229], v[202:205], v[16:19]
	v_mfma_f32_16x16x32_bf16 v[4:7], v[218:221], v[210:213], v[4:7]
	v_mfma_f32_16x16x32_bf16 v[0:3], v[226:229], v[210:213], v[0:3]
	v_mfma_f32_16x16x32_bf16 v[52:55], v[222:225], v[190:193], v[52:55]
	v_mfma_f32_16x16x32_bf16 v[48:51], v[230:233], v[190:193], v[48:51]
	v_mfma_f32_16x16x32_bf16 v[36:39], v[222:225], v[198:201], v[36:39]
	v_mfma_f32_16x16x32_bf16 v[32:35], v[230:233], v[198:201], v[32:35]
	v_mfma_f32_16x16x32_bf16 v[20:23], v[222:225], v[206:209], v[20:23]
	v_mfma_f32_16x16x32_bf16 v[16:19], v[230:233], v[206:209], v[16:19]
	v_mfma_f32_16x16x32_bf16 v[4:7], v[222:225], v[214:217], v[4:7]
	v_mfma_f32_16x16x32_bf16 v[0:3], v[230:233], v[214:217], v[0:3]
	s_setprio 0
	s_add_i32 s37, s37, 2
	s_add_u32 s31, s31, 0x100
	s_addc_u32 s33, s33, 0
	s_cmp_gt_u32 s37, 29
	s_mov_b64 s[46:47], s[48:49]
	s_barrier
	s_cbranch_scc0 .LBB0_81
	v_lshl_add_u32 v146, s44, 8, v142
	v_min_i32_e32 v147, 0x4000, v146
	v_lshl_or_b32 v140, s23, 8, v144
	v_ashrrev_i32_e32 v147, 12, v147
	v_ashrrev_i32_e32 v141, 31, v140
	v_mul_hi_i32_i24_e32 v149, 0xc000, v147
	v_mul_i32_i24_e32 v148, 0xc000, v147
	v_lshl_add_u64 v[148:149], s[0:1], 0, v[148:149]
	v_lshlrev_b64 v[140:141], 2, v[140:141]
	s_movk_i32 s3, 0x4000
	v_lshl_add_u64 v[248:249], v[148:149], 0, v[140:141]
	global_load_dwordx4 v[190:193], v[248:249], off
	global_load_dwordx4 v[194:197], v[248:249], off offset:64
	global_load_dwordx4 v[198:201], v[248:249], off offset:512
	global_load_dwordx4 v[202:205], v[248:249], off offset:576
	v_cmp_gt_i32_e32 vcc, s3, v146
	v_add_u32_e32 v155, 0xffffc000, v146
	v_mov_b32_e32 v147, s7
	v_mov_b32_e32 v148, s83
	v_mov_b32_e32 v149, s6
	v_mov_b32_e32 v150, s82
	v_mov_b32_e32 v151, s58
	v_mov_b32_e32 v152, s65
	v_mov_b32_e32 v153, s59
	v_mov_b32_e32 v154, s66
	v_cndmask_b32_e32 v158, v155, v146, vcc
	v_cndmask_b32_e32 v165, v147, v148, vcc
	v_cndmask_b32_e32 v164, v149, v150, vcc
	v_cndmask_b32_e32 v163, v151, v152, vcc
	v_cndmask_b32_e32 v162, v153, v154, vcc
	v_mov_b32_e32 v157, 0
	v_lshl_add_u64 v[164:165], v[164:165], 0, v[140:141]
	v_lshl_add_u64 v[162:163], v[162:163], 0, v[140:141]
	s_mov_b32 s23, s2
	s_mov_b32 s44, s36
	s_mov_b64 s[48:49], s[42:43]
	s_mov_b64 s[46:47], s[40:41]
	v_mov_b32_e32 v156, v158
	v_lshlrev_b64 v[160:161], 13, v[156:157]
	v_lshl_add_u64 v[244:245], v[160:161], 0, v[162:163]
	global_load_dwordx4 v[206:209], v[244:245], off
	global_load_dwordx4 v[210:213], v[244:245], off offset:64
	global_load_dwordx4 v[214:217], v[244:245], off offset:512
	global_load_dwordx4 v[218:221], v[244:245], off offset:576
	v_add_u32_e32 v156, 0x10, v158
	v_lshlrev_b64 v[160:161], 13, v[156:157]
	v_lshl_add_u64 v[244:245], v[160:161], 0, v[162:163]
	global_load_dwordx4 v[222:225], v[244:245], off
	global_load_dwordx4 v[226:229], v[244:245], off offset:64
	global_load_dwordx4 v[230:233], v[244:245], off offset:512
	global_load_dwordx4 v[234:237], v[244:245], off offset:576
	v_mov_b32_e32 v156, v158
	v_lshlrev_b64 v[160:161], 13, v[156:157]
	v_lshl_add_u64 v[246:247], v[160:161], 0, v[164:165]
	s_waitcnt vmcnt(4)
	v_pk_fma_f32 v[126:127], v[126:127], v[192:193], v[208:209]
	v_pk_fma_f32 v[124:125], v[124:125], v[190:191], v[206:207]
	v_pk_fma_f32 v[122:123], v[122:123], v[196:197], v[212:213]
	v_pk_fma_f32 v[120:121], v[120:121], v[194:195], v[210:211]
	v_pk_fma_f32 v[118:119], v[118:119], v[200:201], v[216:217]
	v_pk_fma_f32 v[116:117], v[116:117], v[198:199], v[214:215]
	v_pk_fma_f32 v[114:115], v[114:115], v[204:205], v[220:221]
	v_pk_fma_f32 v[112:113], v[112:113], v[202:203], v[218:219]
	global_store_dwordx4 v[246:247], v[124:127], off
	global_store_dwordx4 v[246:247], v[120:123], off offset:64
	global_store_dwordx4 v[246:247], v[116:119], off offset:512
	global_store_dwordx4 v[246:247], v[112:115], off offset:576
	v_add_u32_e32 v156, 0x20, v158
	v_lshlrev_b64 v[160:161], 13, v[156:157]
	v_lshl_add_u64 v[244:245], v[160:161], 0, v[162:163]
	global_load_dwordx4 v[206:209], v[244:245], off
	global_load_dwordx4 v[210:213], v[244:245], off offset:64
	global_load_dwordx4 v[214:217], v[244:245], off offset:512
	global_load_dwordx4 v[218:221], v[244:245], off offset:576
	v_add_u32_e32 v156, 0x10, v158
	v_lshlrev_b64 v[160:161], 13, v[156:157]
	v_lshl_add_u64 v[246:247], v[160:161], 0, v[164:165]
	s_waitcnt vmcnt(4)
;   __device__ __forceinline__ void operator()(const f32x4 (&acc)[2][2][4][2], const Unit& u, int wr, int wc, int fr, int fq) const {
;     const int row0 = u.pm * BM + wr * 64 + fr, col0 = u.pn * BM + wc * 32 + 4 * fq;
; #pragma unroll
;     for (int ai = 0; ai < 2; ++ai)
; #pragma unroll
;       for (int m = 0; m < 4; ++m) {
;         const int row = row0 + ai * HALF + m * 16;
;         const float* gp = gate + (size_t)condof(row) * 6 * D + col0;
;         const float* hold; float* hnew;
;         if (row < NX) { hnew = out + (size_t)row * D + col0; hold = xin ? xin + (size_t)row * D + col0 : hnew; }
;         else { hnew = hc + (size_t)(row - NX) * D + col0; hold = cin ? cin + (size_t)(row - NX) * D + col0 : hnew; }
; #pragma unroll
;         for (int bj = 0; bj < 2; ++bj)
; #pragma unroll
;           for (int n = 0; n < 2; ++n) {
;             f32x4 h = *reinterpret_cast<const f32x4*>(hold + bj * HALF + n * 16);
;             f32x4 g = *reinterpret_cast<const f32x4*>(gp + bj * HALF + n * 16);
;             *reinterpret_cast<f32x4*>(hnew + bj * HALF + n * 16) = h + g * acc[ai][bj][m][n];
;           }
;       }
;   }
	v_pk_fma_f32 v[110:111], v[110:111], v[192:193], v[224:225]
	v_pk_fma_f32 v[108:109], v[108:109], v[190:191], v[222:223]
	v_pk_fma_f32 v[106:107], v[106:107], v[196:197], v[228:229]
	v_pk_fma_f32 v[104:105], v[104:105], v[194:195], v[226:227]
	v_pk_fma_f32 v[102:103], v[102:103], v[200:201], v[232:233]
	v_pk_fma_f32 v[100:101], v[100:101], v[198:199], v[230:231]
	v_pk_fma_f32 v[98:99], v[98:99], v[204:205], v[236:237]
	v_pk_fma_f32 v[96:97], v[96:97], v[202:203], v[234:235]
	global_store_dwordx4 v[246:247], v[108:111], off
	global_store_dwordx4 v[246:247], v[104:107], off offset:64
	global_store_dwordx4 v[246:247], v[100:103], off offset:512
	global_store_dwordx4 v[246:247], v[96:99], off offset:576
	v_add_u32_e32 v156, 0x30, v158
	v_lshlrev_b64 v[160:161], 13, v[156:157]
	v_lshl_add_u64 v[244:245], v[160:161], 0, v[162:163]
	global_load_dwordx4 v[222:225], v[244:245], off
	global_load_dwordx4 v[226:229], v[244:245], off offset:64
	global_load_dwordx4 v[230:233], v[244:245], off offset:512
	global_load_dwordx4 v[234:237], v[244:245], off offset:576
	v_add_u32_e32 v156, 0x20, v158
	v_lshlrev_b64 v[160:161], 13, v[156:157]
	v_lshl_add_u64 v[246:247], v[160:161], 0, v[164:165]
	s_waitcnt vmcnt(4)
	v_pk_fma_f32 v[94:95], v[94:95], v[192:193], v[208:209]
	v_pk_fma_f32 v[92:93], v[92:93], v[190:191], v[206:207]
	v_pk_fma_f32 v[90:91], v[90:91], v[196:197], v[212:213]
	v_pk_fma_f32 v[88:89], v[88:89], v[194:195], v[210:211]
	v_pk_fma_f32 v[86:87], v[86:87], v[200:201], v[216:217]
	v_pk_fma_f32 v[84:85], v[84:85], v[198:199], v[214:215]
	v_pk_fma_f32 v[82:83], v[82:83], v[204:205], v[220:221]
	v_pk_fma_f32 v[80:81], v[80:81], v[202:203], v[218:219]
	global_store_dwordx4 v[246:247], v[92:95], off
	global_store_dwordx4 v[246:247], v[88:91], off offset:64
	global_store_dwordx4 v[246:247], v[84:87], off offset:512
	global_store_dwordx4 v[246:247], v[80:83], off offset:576
	v_add_u32_e32 v156, 0x80, v158
	v_lshlrev_b64 v[160:161], 13, v[156:157]
	v_lshl_add_u64 v[244:245], v[160:161], 0, v[162:163]
	global_load_dwordx4 v[206:209], v[244:245], off
	global_load_dwordx4 v[210:213], v[244:245], off offset:64
	global_load_dwordx4 v[214:217], v[244:245], off offset:512
	global_load_dwordx4 v[218:221], v[244:245], off offset:576
	v_add_u32_e32 v156, 0x30, v158
	v_lshlrev_b64 v[160:161], 13, v[156:157]
	v_lshl_add_u64 v[246:247], v[160:161], 0, v[164:165]
	s_waitcnt vmcnt(4)
	v_pk_fma_f32 v[78:79], v[78:79], v[192:193], v[224:225]
	v_pk_fma_f32 v[76:77], v[76:77], v[190:191], v[222:223]
	v_pk_fma_f32 v[74:75], v[74:75], v[196:197], v[228:229]
	v_pk_fma_f32 v[72:73], v[72:73], v[194:195], v[226:227]
	v_pk_fma_f32 v[70:71], v[70:71], v[200:201], v[232:233]
	v_pk_fma_f32 v[68:69], v[68:69], v[198:199], v[230:231]
	v_pk_fma_f32 v[66:67], v[66:67], v[204:205], v[236:237]
	v_pk_fma_f32 v[64:65], v[64:65], v[202:203], v[234:235]
	global_store_dwordx4 v[246:247], v[76:79], off
	global_store_dwordx4 v[246:247], v[72:75], off offset:64
	global_store_dwordx4 v[246:247], v[68:71], off offset:512
	global_store_dwordx4 v[246:247], v[64:67], off offset:576
	v_add_u32_e32 v156, 0x90, v158
	v_lshlrev_b64 v[160:161], 13, v[156:157]
	v_lshl_add_u64 v[244:245], v[160:161], 0, v[162:163]
	global_load_dwordx4 v[222:225], v[244:245], off
	global_load_dwordx4 v[226:229], v[244:245], off offset:64
	global_load_dwordx4 v[230:233], v[244:245], off offset:512
	global_load_dwordx4 v[234:237], v[244:245], off offset:576
	v_add_u32_e32 v156, 0x80, v158
	v_lshlrev_b64 v[160:161], 13, v[156:157]
	v_lshl_add_u64 v[246:247], v[160:161], 0, v[164:165]
	s_waitcnt vmcnt(4)
;   __device__ __forceinline__ void operator()(const f32x4 (&acc)[2][2][4][2], const Unit& u, int wr, int wc, int fr, int fq) const {
;     const int row0 = u.pm * BM + wr * 64 + fr, col0 = u.pn * BM + wc * 32 + 4 * fq;
; #pragma unroll
;     for (int ai = 0; ai < 2; ++ai)
; #pragma unroll
;       for (int m = 0; m < 4; ++m) {
;         const int row = row0 + ai * HALF + m * 16;
;         const float* gp = gate + (size_t)condof(row) * 6 * D + col0;
;         const float* hold; float* hnew;
;         if (row < NX) { hnew = out + (size_t)row * D + col0; hold = xin ? xin + (size_t)row * D + col0 : hnew; }
;         else { hnew = hc + (size_t)(row - NX) * D + col0; hold = cin ? cin + (size_t)(row - NX) * D + col0 : hnew; }
; #pragma unroll
;         for (int bj = 0; bj < 2; ++bj)
; #pragma unroll
;           for (int n = 0; n < 2; ++n) {
;             f32x4 h = *reinterpret_cast<const f32x4*>(hold + bj * HALF + n * 16);
;             f32x4 g = *reinterpret_cast<const f32x4*>(gp + bj * HALF + n * 16);
;             *reinterpret_cast<f32x4*>(hnew + bj * HALF + n * 16) = h + g * acc[ai][bj][m][n];
;           }
;       }
;   }
; template <class Epi>
; __device__ __forceinline__ void gemm_phase(LAS unsigned char* lds, const u16* gA, const u16* gBt, int M, int N, int K, const Epi& E) {
;     ...
;     E(acc, cur, wr, wc, fr, fq);
;     if (!has_next) break;
	v_pk_fma_f32 v[62:63], v[62:63], v[192:193], v[208:209]
	v_pk_fma_f32 v[60:61], v[60:61], v[190:191], v[206:207]
	v_pk_fma_f32 v[58:59], v[58:59], v[196:197], v[212:213]
	v_pk_fma_f32 v[56:57], v[56:57], v[194:195], v[210:211]
	v_pk_fma_f32 v[54:55], v[54:55], v[200:201], v[216:217]
	v_pk_fma_f32 v[52:53], v[52:53], v[198:199], v[214:215]
	v_pk_fma_f32 v[50:51], v[50:51], v[204:205], v[220:221]
	v_pk_fma_f32 v[48:49], v[48:49], v[202:203], v[218:219]
	global_store_dwordx4 v[246:247], v[60:63], off
	global_store_dwordx4 v[246:247], v[56:59], off offset:64
	global_store_dwordx4 v[246:247], v[52:55], off offset:512
	global_store_dwordx4 v[246:247], v[48:51], off offset:576
	v_add_u32_e32 v156, 0xa0, v158
	v_lshlrev_b64 v[160:161], 13, v[156:157]
	v_lshl_add_u64 v[244:245], v[160:161], 0, v[162:163]
	global_load_dwordx4 v[206:209], v[244:245], off
	global_load_dwordx4 v[210:213], v[244:245], off offset:64
	global_load_dwordx4 v[214:217], v[244:245], off offset:512
	global_load_dwordx4 v[218:221], v[244:245], off offset:576
	v_add_u32_e32 v156, 0x90, v158
	v_lshlrev_b64 v[160:161], 13, v[156:157]
	v_lshl_add_u64 v[246:247], v[160:161], 0, v[164:165]
	s_waitcnt vmcnt(4)
	v_pk_fma_f32 v[46:47], v[46:47], v[192:193], v[224:225]
	v_pk_fma_f32 v[44:45], v[44:45], v[190:191], v[222:223]
	v_pk_fma_f32 v[42:43], v[42:43], v[196:197], v[228:229]
	v_pk_fma_f32 v[40:41], v[40:41], v[194:195], v[226:227]
	v_pk_fma_f32 v[38:39], v[38:39], v[200:201], v[232:233]
	v_pk_fma_f32 v[36:37], v[36:37], v[198:199], v[230:231]
	v_pk_fma_f32 v[34:35], v[34:35], v[204:205], v[236:237]
	v_pk_fma_f32 v[32:33], v[32:33], v[202:203], v[234:235]
	global_store_dwordx4 v[246:247], v[44:47], off
	global_store_dwordx4 v[246:247], v[40:43], off offset:64
	global_store_dwordx4 v[246:247], v[36:39], off offset:512
	global_store_dwordx4 v[246:247], v[32:35], off offset:576
	v_add_u32_e32 v156, 0xb0, v158
	v_lshlrev_b64 v[160:161], 13, v[156:157]
	v_lshl_add_u64 v[244:245], v[160:161], 0, v[162:163]
	global_load_dwordx4 v[222:225], v[244:245], off
	global_load_dwordx4 v[226:229], v[244:245], off offset:64
	global_load_dwordx4 v[230:233], v[244:245], off offset:512
	global_load_dwordx4 v[234:237], v[244:245], off offset:576
	v_add_u32_e32 v156, 0xa0, v158
	v_lshlrev_b64 v[160:161], 13, v[156:157]
	v_lshl_add_u64 v[246:247], v[160:161], 0, v[164:165]
	s_waitcnt vmcnt(4)
	v_pk_fma_f32 v[30:31], v[30:31], v[192:193], v[208:209]
	v_pk_fma_f32 v[28:29], v[28:29], v[190:191], v[206:207]
	v_pk_fma_f32 v[26:27], v[26:27], v[196:197], v[212:213]
	v_pk_fma_f32 v[24:25], v[24:25], v[194:195], v[210:211]
	v_pk_fma_f32 v[22:23], v[22:23], v[200:201], v[216:217]
	v_pk_fma_f32 v[20:21], v[20:21], v[198:199], v[214:215]
	v_pk_fma_f32 v[18:19], v[18:19], v[204:205], v[220:221]
	v_pk_fma_f32 v[16:17], v[16:17], v[202:203], v[218:219]
	global_store_dwordx4 v[246:247], v[28:31], off
	global_store_dwordx4 v[246:247], v[24:27], off offset:64
	global_store_dwordx4 v[246:247], v[20:23], off offset:512
	global_store_dwordx4 v[246:247], v[16:19], off offset:576
	v_add_u32_e32 v156, 0xb0, v158
	v_lshlrev_b64 v[160:161], 13, v[156:157]
	v_lshl_add_u64 v[246:247], v[160:161], 0, v[164:165]
	s_waitcnt vmcnt(0)
	v_pk_fma_f32 v[14:15], v[14:15], v[192:193], v[224:225]
	v_pk_fma_f32 v[12:13], v[12:13], v[190:191], v[222:223]
	v_pk_fma_f32 v[10:11], v[10:11], v[196:197], v[228:229]
	v_pk_fma_f32 v[8:9], v[8:9], v[194:195], v[226:227]
	v_pk_fma_f32 v[6:7], v[6:7], v[200:201], v[232:233]
	v_pk_fma_f32 v[4:5], v[4:5], v[198:199], v[230:231]
	v_pk_fma_f32 v[2:3], v[2:3], v[204:205], v[236:237]
	v_pk_fma_f32 v[0:1], v[0:1], v[202:203], v[234:235]
	global_store_dwordx4 v[246:247], v[12:15], off
	global_store_dwordx4 v[246:247], v[8:11], off offset:64
	global_store_dwordx4 v[246:247], v[4:7], off offset:512
	global_store_dwordx4 v[246:247], v[0:3], off offset:576
	s_and_b64 vcc, exec, s[38:39]
	s_cbranch_vccz .LBB0_78
	s_waitcnt vmcnt(0)
	v_readlane_b32 s70, v238, 38
	v_readlane_b32 s64, v238, 52
	s_cmpk_gt_u32 s54, 0xff
	v_readlane_b32 s71, v238, 39
	s_movk_i32 s75, 0x3000
	s_movk_i32 s78, 0x2000
	v_readlane_b32 s65, v238, 53
	s_cbranch_scc1 .LBB0_85
	s_barrier

; __device__ void phase_gdnprep(const P& p, int l, float* lds) {
;     ...
;   float* aup_s = lds;
;   for (int e = tid; e < 2 * 16 * 256; e += NTHR) aup_s[e] = p.gla_a_up[(size_t)l * 2 * 16 * 256 + e];
;   float4 abias[2];
;   abias[0] = *reinterpret_cast<const float4*>(p.gla_a_b + ((size_t)l * 2 + 0) * 256 + lane * 4);
;   abias[1] = *reinterpret_cast<const float4*>(p.gla_a_b + ((size_t)l * 2 + 1) * 256 + lane * 4);
;   const float gA = __expf(p.gdn_a_log[(size_t)l * 8 + (lane & 7)]), gdt = p.gdn_dt_bias[(size_t)l * 8 + (lane & 7)];
;   __syncthreads();
.LBB0_107:
	v_mov_b32_e32 v8, v0
	v_ashrrev_i32_e32 v9, 31, v8
	v_lshl_add_u64 v[8:9], v[8:9], 2, s[40:41]
	global_load_dword v241, v[8:9], off
	v_mov_b32_e32 v6, v1
	v_ashrrev_i32_e32 v7, 31, v6
	v_lshl_add_u64 v[6:7], v[6:7], 2, s[40:41]
	global_load_dword v242, v[6:7], off
	v_add_u32_e32 v8, 0x400, v0
	v_ashrrev_i32_e32 v9, 31, v8
	v_lshl_add_u64 v[8:9], v[8:9], 2, s[40:41]
	global_load_dword v243, v[8:9], off
	v_add_u32_e32 v6, 0x400, v1
	v_ashrrev_i32_e32 v7, 31, v6
	v_lshl_add_u64 v[6:7], v[6:7], 2, s[40:41]
	global_load_dword v244, v[6:7], off
	v_add_u32_e32 v8, 0x800, v0
	v_ashrrev_i32_e32 v9, 31, v8
	v_lshl_add_u64 v[8:9], v[8:9], 2, s[40:41]
	global_load_dword v245, v[8:9], off
	v_add_u32_e32 v6, 0x800, v1
	v_ashrrev_i32_e32 v7, 31, v6
	v_lshl_add_u64 v[6:7], v[6:7], 2, s[40:41]
	global_load_dword v246, v[6:7], off
	v_add_u32_e32 v8, 0xc00, v0
	v_ashrrev_i32_e32 v9, 31, v8
	v_lshl_add_u64 v[8:9], v[8:9], 2, s[40:41]
	global_load_dword v247, v[8:9], off
	v_add_u32_e32 v6, 0xc00, v1
	v_ashrrev_i32_e32 v7, 31, v6
	v_lshl_add_u64 v[6:7], v[6:7], 2, s[40:41]
	global_load_dword v248, v[6:7], off
	v_add_u32_e32 v8, 0x1000, v0
	v_ashrrev_i32_e32 v9, 31, v8
	v_lshl_add_u64 v[8:9], v[8:9], 2, s[40:41]
	global_load_dword v249, v[8:9], off
	v_add_u32_e32 v6, 0x1000, v1
	v_ashrrev_i32_e32 v7, 31, v6
	v_lshl_add_u64 v[6:7], v[6:7], 2, s[40:41]
	global_load_dword v250, v[6:7], off
	v_add_u32_e32 v8, 0x1400, v0
	v_ashrrev_i32_e32 v9, 31, v8
	v_lshl_add_u64 v[8:9], v[8:9], 2, s[40:41]
	global_load_dword v251, v[8:9], off
	v_add_u32_e32 v6, 0x1400, v1
	v_ashrrev_i32_e32 v7, 31, v6
	v_lshl_add_u64 v[6:7], v[6:7], 2, s[40:41]
	global_load_dword v252, v[6:7], off
	v_add_u32_e32 v8, 0x1800, v0
	v_ashrrev_i32_e32 v9, 31, v8
	v_lshl_add_u64 v[8:9], v[8:9], 2, s[40:41]
	global_load_dword v253, v[8:9], off
	v_add_u32_e32 v6, 0x1800, v1
	v_ashrrev_i32_e32 v7, 31, v6
	v_lshl_add_u64 v[6:7], v[6:7], 2, s[40:41]
	global_load_dword v254, v[6:7], off
	v_add_u32_e32 v8, 0x1c00, v0
	v_ashrrev_i32_e32 v9, 31, v8
	v_lshl_add_u64 v[8:9], v[8:9], 2, s[40:41]
	global_load_dword v255, v[8:9], off
	v_add_u32_e32 v6, 0x1c00, v1
	v_ashrrev_i32_e32 v7, 31, v6
	v_lshl_add_u64 v[6:7], v[6:7], 2, s[40:41]
	global_load_dword v6, v[6:7], off
	v_add_u32_e32 v4, -8, v4
	s_add_i32 s23, s23, 16
	v_cmp_eq_u32_e32 vcc, 0, v4
	s_or_b64 s[44:45], vcc, s[44:45]
	v_add_u32_e32 v1, 0x2000, v1
	v_add_u32_e32 v0, 0x2000, v0
	s_waitcnt vmcnt(0)
	ds_write2st64_b32 v5, v241, v242 offset1:8
	ds_write2st64_b32 v5, v243, v244 offset0:16 offset1:24
	ds_write2st64_b32 v5, v245, v246 offset0:32 offset1:40
	ds_write2st64_b32 v5, v247, v248 offset0:48 offset1:56
	ds_write2st64_b32 v5, v249, v250 offset0:64 offset1:72
	ds_write2st64_b32 v5, v251, v252 offset0:80 offset1:88
	ds_write2st64_b32 v5, v253, v254 offset0:96 offset1:104
	ds_write2st64_b32 v5, v255, v6 offset0:112 offset1:120
	v_add_u32_e32 v5, 0x8000, v5
	v_mov_b32_e32 v6, s23
	s_andn2_b64 exec, exec, s[44:45]
	s_cbranch_execnz .LBB0_107
	s_or_b64 exec, exec, s[44:45]
